# attention loop: packed f32 ops split to scalar, branch-0 score tiles kept in VGPRs (no accvgpr reads), row-sum tail rewritten, x+0 folded; EPI_UP stores widened to dwordx4 via permlane32_swap
# speedup vs baseline: 1.0434x; 1.0355x over previous
; DEV uint32_t pk2(float lo, float hi) { f32x2 v; v[0] = lo; v[1] = hi; bf16v2 b = __builtin_convertvector(v, bf16v2); return __builtin_bit_cast(uint32_t, b); }
; DEV float rscale_of(const float* ssq, int m) {
;   const f32x4 a = *(const f32x4*)(ssq + (size_t)m * NPART), b = *(const f32x4*)(ssq + (size_t)m * NPART + 4);
;   const float s = (a[0] + a[1]) + (a[2] + a[3]) + (b[0] + b[1]) + (b[2] + b[3]);
;   return rsqrtf(s * (1.f / DM) + EPS);
; }
; template <int EPI>
; DEV void gemm_tile(CParams& p, int layer, const bf16_t* __restrict__ A, int lda, const bf16_t* __restrict__ Bt, int K, int m0, int n0, int nt, char* lds, const int swave) {
;     ...
;       const float rs = rscale_of(ssq, mc);
;       bf16_t* urow = (bf16_t*)(ws + W_U) + (size_t)mc * DFF;
; #pragma unroll
;       for (int j = 0; j < 4; ++j)
; #pragma unroll
;         for (int g = 0; g < 4; ++g) {
;           const int n = n0 + wn * 128 + j * 32 + 8 * g + 4 * hh;
;           float v0 = fmaxf(acc[j][i][4 * g] * rs, 0.f), v1 = fmaxf(acc[j][i][4 * g + 1] * rs, 0.f), v2 = fmaxf(acc[j][i][4 * g + 2] * rs, 0.f), v3 = fmaxf(acc[j][i][4 * g + 3] * rs, 0.f);
;           u32x2 pk; pk[0] = pk2(v0 * v0, v1 * v1); pk[1] = pk2(v2 * v2, v3 * v3);
;           *(u32x2*)(urow + n) = pk;
;         }
.LBB0_96:
	s_waitcnt vmcnt(0)
	v_mbcnt_lo_u32_b32 v206, -1, 0
	v_mbcnt_hi_u32_b32 v206, -1, v206
	v_and_b32_e32 v206, 32, v206
	v_lshrrev_b32_e32 v206, 2, v206
	v_mov_b32_e32 v207, 0
	s_and_b32 s2, s30, 0xffffff80
	v_or_b32_e32 v0, s66, v28
	v_add_u32_e32 v64, s2, v0
	v_ashrrev_i32_e32 v65, 31, v64
	v_lshlrev_b64 v[0:1], 5, v[64:65]
	v_lshl_add_u64 v[0:1], s[4:5], 0, v[0:1]
	global_load_dwordx4 v[68:71], v[0:1], off
	global_load_dwordx4 v[72:75], v[0:1], off offset:16
	s_waitcnt vmcnt(12)
	v_lshlrev_b64 v[76:77], 13, v[64:65]
	v_accvgpr_read_b32 v48, a192
	v_accvgpr_read_b32 v0, a240
	v_accvgpr_read_b32 v16, a224
	v_accvgpr_read_b32 v32, a208
	v_accvgpr_read_b32 v49, a193
	v_accvgpr_read_b32 v50, a194
	v_accvgpr_read_b32 v51, a195
	v_lshl_or_b32 v66, v66, 2, s8
	v_accvgpr_read_b32 v1, a241
	v_accvgpr_read_b32 v2, a242
	v_accvgpr_read_b32 v3, a243
	v_accvgpr_read_b32 v17, a225
	v_accvgpr_read_b32 v18, a226
	v_accvgpr_read_b32 v19, a227
	v_accvgpr_read_b32 v33, a209
	v_accvgpr_read_b32 v34, a210
	v_accvgpr_read_b32 v35, a211
	v_accvgpr_read_b32 v52, a196
	v_accvgpr_read_b32 v53, a197
	v_accvgpr_read_b32 v54, a198
	v_accvgpr_read_b32 v55, a199
	v_accvgpr_read_b32 v56, a200
	v_accvgpr_read_b32 v57, a201
	v_accvgpr_read_b32 v58, a202
	v_accvgpr_read_b32 v59, a203
	v_accvgpr_read_b32 v60, a204
	v_accvgpr_read_b32 v61, a205
	v_accvgpr_read_b32 v62, a206
	v_accvgpr_read_b32 v63, a207
	v_or_b32_e32 v66, s9, v66
	v_ashrrev_i32_e32 v67, 31, v66
	v_lshlrev_b64 v[66:67], 1, v[66:67]
	v_accvgpr_read_b32 v37, a213
	v_accvgpr_read_b32 v4, a244
	v_accvgpr_read_b32 v5, a245
	v_accvgpr_read_b32 v6, a246
	v_accvgpr_read_b32 v7, a247
	v_accvgpr_read_b32 v20, a228
	v_accvgpr_read_b32 v21, a229
	v_accvgpr_read_b32 v22, a230
	v_accvgpr_read_b32 v23, a231
	v_accvgpr_read_b32 v36, a212
	v_accvgpr_read_b32 v38, a214
	v_accvgpr_read_b32 v39, a215
	v_accvgpr_read_b32 v8, a248
	v_accvgpr_read_b32 v9, a249
	v_accvgpr_read_b32 v10, a250
	v_accvgpr_read_b32 v11, a251
	v_accvgpr_read_b32 v24, a232
	v_accvgpr_read_b32 v25, a233
	v_accvgpr_read_b32 v26, a234
	v_accvgpr_read_b32 v27, a235
	v_accvgpr_read_b32 v40, a216
	v_accvgpr_read_b32 v41, a217
	v_accvgpr_read_b32 v42, a218
	v_accvgpr_read_b32 v43, a219
	v_accvgpr_read_b32 v12, a252
	v_accvgpr_read_b32 v13, a253
	v_accvgpr_read_b32 v14, a254
	v_accvgpr_read_b32 v15, a255
	v_accvgpr_read_b32 v28, a236
	v_accvgpr_read_b32 v29, a237
	v_accvgpr_read_b32 v30, a238
	v_accvgpr_read_b32 v31, a239
	v_accvgpr_read_b32 v44, a220
	v_accvgpr_read_b32 v45, a221
	v_accvgpr_read_b32 v46, a222
	v_accvgpr_read_b32 v47, a223
	s_add_i32 s29, s29, s11
	s_cmpk_gt_i32 s29, 0x7ff
	s_waitcnt vmcnt(1)
	v_mov_b32_e32 v78, v69
	v_mov_b32_e32 v79, v70
	v_mov_b32_e32 v69, v71
	s_waitcnt vmcnt(0)
	v_mov_b32_e32 v70, v74
	v_mov_b32_e32 v71, v72
	v_mov_b32_e32 v72, v75
	v_pk_add_f32 v[68:69], v[78:79], v[68:69]
	v_pk_add_f32 v[70:71], v[70:71], v[72:73]
	v_add_f32_e32 v65, v68, v69
	v_add_f32_e32 v65, v65, v71
	v_add_f32_e32 v65, v70, v65
	v_fmamk_f32 v65, v65, 0x3a800000, v242
	v_mul_f32_e32 v68, 0x4b800000, v65
	v_cmp_gt_f32_e32 vcc, s25, v65
	s_nop 1
	v_cndmask_b32_e32 v65, v65, v68, vcc
	v_rsq_f32_e32 v65, v65
	v_lshl_add_u64 v[68:69], s[6:7], 0, v[76:77]
	v_lshl_add_u64 v[68:69], v[68:69], 0, v[66:67]
	v_mul_f32_e32 v70, 0x45800000, v65
	v_cndmask_b32_e32 v65, v65, v70, vcc
	v_mul_f32_e32 v48, v48, v65
	v_mul_f32_e32 v49, v49, v65
	v_mul_f32_e32 v50, v50, v65
	v_mul_f32_e32 v51, v51, v65
	v_mul_f32_e32 v52, v52, v65
	v_mul_f32_e32 v53, v53, v65
	v_mul_f32_e32 v54, v54, v65
	v_mul_f32_e32 v55, v55, v65
	v_mul_f32_e32 v56, v56, v65
	v_mul_f32_e32 v57, v57, v65
	v_mul_f32_e32 v58, v58, v65
	v_mul_f32_e32 v59, v59, v65
	v_mul_f32_e32 v60, v60, v65
	v_mul_f32_e32 v61, v61, v65
	v_mul_f32_e32 v62, v62, v65
	v_mul_f32_e32 v63, v63, v65
	v_mul_f32_e32 v70, v32, v65
	v_mul_f32_e32 v71, v33, v65
	v_mul_f32_e32 v72, v34, v65
	v_mul_f32_e32 v73, v35, v65
	v_max_f32_e32 v32, 0, v48
	v_max_f32_e32 v33, 0, v49
	v_max_f32_e32 v34, 0, v50
	v_max_f32_e32 v35, 0, v51
	v_mul_f32_e32 v16, v16, v65
	v_mul_f32_e32 v17, v17, v65
	v_mul_f32_e32 v18, v18, v65
	v_mul_f32_e32 v19, v19, v65
	v_mul_f32_e32 v0, v0, v65
	v_mul_f32_e32 v1, v1, v65
	v_mul_f32_e32 v2, v2, v65
	v_mul_f32_e32 v3, v3, v65
	v_max_f32_e32 v48, 0, v52
	v_max_f32_e32 v49, 0, v53
	v_max_f32_e32 v50, 0, v54
	v_max_f32_e32 v51, 0, v55
	v_max_f32_e32 v52, 0, v56
	v_max_f32_e32 v53, 0, v57
	v_max_f32_e32 v54, 0, v58
	v_max_f32_e32 v55, 0, v59
	v_max_f32_e32 v56, 0, v60
	v_max_f32_e32 v57, 0, v61
	v_max_f32_e32 v58, 0, v62
	v_max_f32_e32 v59, 0, v63
	v_max_f32_e32 v60, 0, v70
	v_max_f32_e32 v61, 0, v71
	v_max_f32_e32 v62, 0, v72
	v_max_f32_e32 v63, 0, v73
	v_pk_mul_f32 v[32:33], v[32:33], v[32:33]
	v_pk_mul_f32 v[34:35], v[34:35], v[34:35]
	v_max_f32_e32 v16, 0, v16
	v_max_f32_e32 v17, 0, v17
	v_max_f32_e32 v18, 0, v18
	v_max_f32_e32 v19, 0, v19
	v_max_f32_e32 v0, 0, v0
	v_max_f32_e32 v1, 0, v1
	v_max_f32_e32 v2, 0, v2
	v_max_f32_e32 v3, 0, v3
	v_pk_mul_f32 v[48:49], v[48:49], v[48:49]
	v_pk_mul_f32 v[50:51], v[50:51], v[50:51]
	v_pk_mul_f32 v[52:53], v[52:53], v[52:53]
	v_pk_mul_f32 v[54:55], v[54:55], v[54:55]
	v_pk_mul_f32 v[56:57], v[56:57], v[56:57]
	v_pk_mul_f32 v[58:59], v[58:59], v[58:59]
	v_pk_mul_f32 v[60:61], v[60:61], v[60:61]
	v_pk_mul_f32 v[62:63], v[62:63], v[62:63]
	v_cvt_pk_bf16_f32 v208, v32, v33
	v_cvt_pk_bf16_f32 v209, v34, v35
	v_pk_mul_f32 v[16:17], v[16:17], v[16:17]
	v_pk_mul_f32 v[18:19], v[18:19], v[18:19]
	v_pk_mul_f32 v[0:1], v[0:1], v[0:1]
	v_pk_mul_f32 v[2:3], v[2:3], v[2:3]
	v_cvt_pk_bf16_f32 v210, v48, v49
	v_cvt_pk_bf16_f32 v211, v50, v51
	v_cvt_pk_bf16_f32 v212, v52, v53
; DEV uint32_t pk2(float lo, float hi) { f32x2 v; v[0] = lo; v[1] = hi; bf16v2 b = __builtin_convertvector(v, bf16v2); return __builtin_bit_cast(uint32_t, b); }
; template <int EPI>
; DEV void gemm_tile(CParams& p, int layer, const bf16_t* __restrict__ A, int lda, const bf16_t* __restrict__ Bt, int K, int m0, int n0, int nt, char* lds, const int swave) {
;     ...
;       const float rs = rscale_of(ssq, mc);
;       bf16_t* urow = (bf16_t*)(ws + W_U) + (size_t)mc * DFF;
; #pragma unroll
;       for (int j = 0; j < 4; ++j)
; #pragma unroll
;         for (int g = 0; g < 4; ++g) {
;           const int n = n0 + wn * 128 + j * 32 + 8 * g + 4 * hh;
;           float v0 = fmaxf(acc[j][i][4 * g] * rs, 0.f), v1 = fmaxf(acc[j][i][4 * g + 1] * rs, 0.f), v2 = fmaxf(acc[j][i][4 * g + 2] * rs, 0.f), v3 = fmaxf(acc[j][i][4 * g + 3] * rs, 0.f);
;           u32x2 pk; pk[0] = pk2(v0 * v0, v1 * v1); pk[1] = pk2(v2 * v2, v3 * v3);
;           *(u32x2*)(urow + n) = pk;
;         }
	v_cvt_pk_bf16_f32 v213, v54, v55
	v_cvt_pk_bf16_f32 v214, v56, v57
	v_cvt_pk_bf16_f32 v215, v58, v59
	v_cvt_pk_bf16_f32 v216, v60, v61
	v_cvt_pk_bf16_f32 v217, v62, v63
	s_nop 1
	v_permlane32_swap_b32_e32 v208, v210
	v_permlane32_swap_b32_e32 v209, v211
	v_lshl_add_u64 v[204:205], v[68:69], 0, v[206:207]
	global_store_dwordx4 v[204:205], v[208:211], off
	s_nop 1
	v_permlane32_swap_b32_e32 v212, v214
	v_permlane32_swap_b32_e32 v213, v215
	v_lshl_add_u64 v[204:205], v[68:69], 0, v[206:207]
	global_store_dwordx4 v[204:205], v[212:215], off offset:32
	v_mul_f32_e32 v32, v37, v65
	v_cvt_pk_bf16_f32 v224, v16, v17
	v_cvt_pk_bf16_f32 v225, v18, v19
	v_cvt_pk_bf16_f32 v232, v0, v1
	v_cvt_pk_bf16_f32 v233, v2, v3
	v_mul_f32_e32 v36, v36, v65
	v_max_f32_e32 v37, 0, v32
	v_mul_f32_e32 v32, v38, v65
	v_mul_f32_e32 v33, v39, v65
	v_mul_f32_e32 v16, v20, v65
	v_mul_f32_e32 v17, v21, v65
	v_mul_f32_e32 v18, v22, v65
	v_mul_f32_e32 v19, v23, v65
	v_mul_f32_e32 v0, v4, v65
	v_mul_f32_e32 v1, v5, v65
	v_mul_f32_e32 v2, v6, v65
	v_mul_f32_e32 v3, v7, v65
	v_max_f32_e32 v36, 0, v36
	v_max_f32_e32 v32, 0, v32
	v_max_f32_e32 v33, 0, v33
	v_max_f32_e32 v16, 0, v16
	v_max_f32_e32 v17, 0, v17
	v_max_f32_e32 v18, 0, v18
	v_max_f32_e32 v19, 0, v19
	v_max_f32_e32 v0, 0, v0
	v_max_f32_e32 v1, 0, v1
	v_max_f32_e32 v2, 0, v2
	v_max_f32_e32 v3, 0, v3
	v_pk_mul_f32 v[34:35], v[36:37], v[36:37]
	v_pk_mul_f32 v[32:33], v[32:33], v[32:33]
	v_pk_mul_f32 v[16:17], v[16:17], v[16:17]
	v_pk_mul_f32 v[18:19], v[18:19], v[18:19]
	v_pk_mul_f32 v[0:1], v[0:1], v[0:1]
	v_pk_mul_f32 v[2:3], v[2:3], v[2:3]
	v_cvt_pk_bf16_f32 v218, v34, v35
	v_cvt_pk_bf16_f32 v219, v32, v33
	v_cvt_pk_bf16_f32 v226, v16, v17
	v_cvt_pk_bf16_f32 v227, v18, v19
	v_cvt_pk_bf16_f32 v234, v0, v1
	v_cvt_pk_bf16_f32 v235, v2, v3
	s_nop 1
	v_permlane32_swap_b32_e32 v216, v218
	v_permlane32_swap_b32_e32 v217, v219
	v_lshl_add_u64 v[204:205], v[68:69], 0, v[206:207]
	global_store_dwordx4 v[204:205], v[216:219], off offset:64
	v_mul_f32_e32 v32, v40, v65
	v_mul_f32_e32 v33, v41, v65
	v_mul_f32_e32 v34, v42, v65
	v_mul_f32_e32 v35, v43, v65
	s_nop 1
	v_permlane32_swap_b32_e32 v224, v226
	v_permlane32_swap_b32_e32 v225, v227
	v_lshl_add_u64 v[204:205], v[68:69], 0, v[206:207]
	global_store_dwordx4 v[204:205], v[224:227], off offset:128
	v_mul_f32_e32 v16, v24, v65
	v_mul_f32_e32 v17, v25, v65
	v_mul_f32_e32 v18, v26, v65
	v_mul_f32_e32 v19, v27, v65
	s_nop 1
	v_permlane32_swap_b32_e32 v232, v234
	v_permlane32_swap_b32_e32 v233, v235
	v_lshl_add_u64 v[204:205], v[68:69], 0, v[206:207]
	global_store_dwordx4 v[204:205], v[232:235], off offset:192
	v_mul_f32_e32 v0, v8, v65
	v_mul_f32_e32 v1, v9, v65
	v_mul_f32_e32 v2, v10, v65
	v_mul_f32_e32 v3, v11, v65
	v_max_f32_e32 v32, 0, v32
	v_max_f32_e32 v33, 0, v33
	v_max_f32_e32 v34, 0, v34
	v_max_f32_e32 v35, 0, v35
	v_max_f32_e32 v16, 0, v16
	v_max_f32_e32 v17, 0, v17
	v_max_f32_e32 v18, 0, v18
	v_max_f32_e32 v19, 0, v19
	v_max_f32_e32 v0, 0, v0
	v_max_f32_e32 v1, 0, v1
	v_max_f32_e32 v2, 0, v2
	v_max_f32_e32 v3, 0, v3
	v_pk_mul_f32 v[32:33], v[32:33], v[32:33]
	v_pk_mul_f32 v[34:35], v[34:35], v[34:35]
	v_pk_mul_f32 v[16:17], v[16:17], v[16:17]
	v_pk_mul_f32 v[18:19], v[18:19], v[18:19]
	v_pk_mul_f32 v[0:1], v[0:1], v[0:1]
	v_pk_mul_f32 v[2:3], v[2:3], v[2:3]
	v_cvt_pk_bf16_f32 v220, v32, v33
	v_cvt_pk_bf16_f32 v221, v34, v35
	v_cvt_pk_bf16_f32 v228, v16, v17
	v_cvt_pk_bf16_f32 v229, v18, v19
	v_cvt_pk_bf16_f32 v236, v0, v1
	v_cvt_pk_bf16_f32 v237, v2, v3
	v_mul_f32_e32 v32, v44, v65
	v_mul_f32_e32 v33, v45, v65
	v_mul_f32_e32 v34, v46, v65
	v_mul_f32_e32 v35, v47, v65
	v_mul_f32_e32 v16, v28, v65
	v_mul_f32_e32 v17, v29, v65
	v_mul_f32_e32 v18, v30, v65
	v_mul_f32_e32 v19, v31, v65
	v_mul_f32_e32 v0, v12, v65
	v_mul_f32_e32 v1, v13, v65
	v_mul_f32_e32 v2, v14, v65
	v_mul_f32_e32 v3, v15, v65
	v_max_f32_e32 v32, 0, v32
	v_max_f32_e32 v33, 0, v33
	v_max_f32_e32 v34, 0, v34
	v_max_f32_e32 v35, 0, v35
	v_max_f32_e32 v16, 0, v16
	v_max_f32_e32 v17, 0, v17
	v_max_f32_e32 v18, 0, v18
	v_max_f32_e32 v19, 0, v19
	v_max_f32_e32 v0, 0, v0
	v_max_f32_e32 v1, 0, v1
	v_max_f32_e32 v2, 0, v2
	v_max_f32_e32 v3, 0, v3
	v_pk_mul_f32 v[32:33], v[32:33], v[32:33]
	v_pk_mul_f32 v[34:35], v[34:35], v[34:35]
	v_pk_mul_f32 v[16:17], v[16:17], v[16:17]
	v_pk_mul_f32 v[18:19], v[18:19], v[18:19]
	v_pk_mul_f32 v[0:1], v[0:1], v[0:1]
	v_pk_mul_f32 v[2:3], v[2:3], v[2:3]
	v_cvt_pk_bf16_f32 v222, v32, v33
	v_cvt_pk_bf16_f32 v223, v34, v35
	v_cvt_pk_bf16_f32 v230, v16, v17
	v_cvt_pk_bf16_f32 v231, v18, v19
	v_cvt_pk_bf16_f32 v238, v0, v1
	v_cvt_pk_bf16_f32 v239, v2, v3
	s_nop 1
	v_permlane32_swap_b32_e32 v220, v222
	v_permlane32_swap_b32_e32 v221, v223
	v_lshl_add_u64 v[204:205], v[68:69], 0, v[206:207]
	global_store_dwordx4 v[204:205], v[220:223], off offset:96
	s_nop 1
	v_permlane32_swap_b32_e32 v228, v230
	v_permlane32_swap_b32_e32 v229, v231
	v_lshl_add_u64 v[204:205], v[68:69], 0, v[206:207]
	global_store_dwordx4 v[204:205], v[228:231], off offset:160
	s_nop 1
	v_permlane32_swap_b32_e32 v236, v238
	v_permlane32_swap_b32_e32 v237, v239
	v_lshl_add_u64 v[204:205], v[68:69], 0, v[206:207]
	global_store_dwordx4 v[204:205], v[236:239], off offset:224
	v_or_b32_e32 v68, 32, v64
	v_ashrrev_i32_e32 v69, 31, v68
	v_lshlrev_b64 v[0:1], 5, v[68:69]
	v_lshl_add_u64 v[0:1], s[4:5], 0, v[0:1]
	global_load_dwordx4 v[16:19], v[0:1], off
	global_load_dwordx4 v[20:23], v[0:1], off offset:16
	v_accvgpr_read_b32 v48, a128
	v_accvgpr_read_b32 v0, a176
	v_accvgpr_read_b32 v49, a129
	v_accvgpr_read_b32 v1, a177
	v_accvgpr_read_b32 v2, a178
	v_accvgpr_read_b32 v3, a179
	v_accvgpr_read_b32 v32, a144
	v_accvgpr_read_b32 v50, a130
	v_accvgpr_read_b32 v51, a131
	v_accvgpr_read_b32 v33, a145
	v_accvgpr_read_b32 v34, a146
	v_accvgpr_read_b32 v35, a147
	v_lshlrev_b64 v[68:69], 13, v[68:69]
	v_lshl_add_u64 v[68:69], s[6:7], 0, v[68:69]
	v_accvgpr_read_b32 v4, a180
	v_accvgpr_read_b32 v5, a181
	v_accvgpr_read_b32 v6, a182
	v_accvgpr_read_b32 v7, a183
	v_accvgpr_read_b32 v36, a148
	v_accvgpr_read_b32 v37, a149
	v_accvgpr_read_b32 v38, a150
	v_accvgpr_read_b32 v39, a151
	v_accvgpr_read_b32 v52, a132
	v_accvgpr_read_b32 v53, a133
	v_accvgpr_read_b32 v54, a134
	v_accvgpr_read_b32 v55, a135
	v_accvgpr_read_b32 v8, a184
	v_accvgpr_read_b32 v9, a185
	v_accvgpr_read_b32 v10, a186
	v_accvgpr_read_b32 v11, a187
	v_accvgpr_read_b32 v40, a152
	v_accvgpr_read_b32 v41, a153
	v_accvgpr_read_b32 v42, a154
	v_accvgpr_read_b32 v43, a155
	v_accvgpr_read_b32 v56, a136
	v_accvgpr_read_b32 v57, a137
	v_accvgpr_read_b32 v58, a138
	v_accvgpr_read_b32 v59, a139
	v_accvgpr_read_b32 v12, a188
	v_accvgpr_read_b32 v13, a189
	v_accvgpr_read_b32 v14, a190
	v_accvgpr_read_b32 v15, a191
	v_accvgpr_read_b32 v44, a156
	v_accvgpr_read_b32 v45, a157
	v_accvgpr_read_b32 v46, a158
	v_accvgpr_read_b32 v47, a159
	v_accvgpr_read_b32 v60, a140
	v_accvgpr_read_b32 v61, a141
	v_accvgpr_read_b32 v62, a142
	v_accvgpr_read_b32 v63, a143
	s_waitcnt vmcnt(1)
; DEV uint32_t pk2(float lo, float hi) { f32x2 v; v[0] = lo; v[1] = hi; bf16v2 b = __builtin_convertvector(v, bf16v2); return __builtin_bit_cast(uint32_t, b); }
; DEV float rscale_of(const float* ssq, int m) {
;   const f32x4 a = *(const f32x4*)(ssq + (size_t)m * NPART), b = *(const f32x4*)(ssq + (size_t)m * NPART + 4);
;   const float s = (a[0] + a[1]) + (a[2] + a[3]) + (b[0] + b[1]) + (b[2] + b[3]);
;   return rsqrtf(s * (1.f / DM) + EPS);
; }
; template <int EPI>
; DEV void gemm_tile(CParams& p, int layer, const bf16_t* __restrict__ A, int lda, const bf16_t* __restrict__ Bt, int K, int m0, int n0, int nt, char* lds, const int swave) {
;     ...
;       const float rs = rscale_of(ssq, mc);
;       bf16_t* urow = (bf16_t*)(ws + W_U) + (size_t)mc * DFF;
; #pragma unroll
;       for (int j = 0; j < 4; ++j)
; #pragma unroll
;         for (int g = 0; g < 4; ++g) {
;           const int n = n0 + wn * 128 + j * 32 + 8 * g + 4 * hh;
;           float v0 = fmaxf(acc[j][i][4 * g] * rs, 0.f), v1 = fmaxf(acc[j][i][4 * g + 1] * rs, 0.f), v2 = fmaxf(acc[j][i][4 * g + 2] * rs, 0.f), v3 = fmaxf(acc[j][i][4 * g + 3] * rs, 0.f);
;           u32x2 pk; pk[0] = pk2(v0 * v0, v1 * v1); pk[1] = pk2(v2 * v2, v3 * v3);
;           *(u32x2*)(urow + n) = pk;
	v_mov_b32_e32 v24, v17
	v_mov_b32_e32 v25, v18
	v_mov_b32_e32 v17, v19
	v_pk_add_f32 v[16:17], v[24:25], v[16:17]
	s_waitcnt vmcnt(0)
	v_mov_b32_e32 v18, v22
	v_mov_b32_e32 v19, v20
	v_mov_b32_e32 v20, v23
	v_pk_add_f32 v[18:19], v[18:19], v[20:21]
	v_add_f32_e32 v16, v16, v17
	v_add_f32_e32 v16, v16, v19
	v_add_f32_e32 v16, v18, v16
	v_fmamk_f32 v16, v16, 0x3a800000, v242
	v_mul_f32_e32 v17, 0x4b800000, v16
	v_cmp_gt_f32_e32 vcc, s25, v16
	s_nop 1
	v_cndmask_b32_e32 v16, v16, v17, vcc
	v_rsq_f32_e32 v65, v16
	v_accvgpr_read_b32 v16, a160
	v_accvgpr_read_b32 v17, a161
	v_accvgpr_read_b32 v18, a162
	v_mul_f32_e32 v70, 0x45800000, v65
	v_cndmask_b32_e32 v65, v65, v70, vcc
	v_mul_f32_e32 v48, v48, v65
	v_mul_f32_e32 v49, v49, v65
	v_accvgpr_read_b32 v19, a163
	v_max_f32_e32 v48, 0, v48
	v_max_f32_e32 v49, 0, v49
	v_mul_f32_e32 v50, v50, v65
	v_mul_f32_e32 v51, v51, v65
	v_mul_f32_e32 v0, v0, v65
	v_mul_f32_e32 v1, v1, v65
	v_mul_f32_e32 v2, v2, v65
	v_mul_f32_e32 v3, v3, v65
	v_max_f32_e32 v50, 0, v50
	v_max_f32_e32 v51, 0, v51
	v_pk_mul_f32 v[48:49], v[48:49], v[48:49]
	v_mul_f32_e32 v32, v32, v65
	v_mul_f32_e32 v33, v33, v65
	v_mul_f32_e32 v34, v34, v65
	v_mul_f32_e32 v35, v35, v65
	v_mul_f32_e32 v16, v16, v65
	v_mul_f32_e32 v17, v17, v65
	v_mul_f32_e32 v18, v18, v65
	v_mul_f32_e32 v19, v19, v65
	v_max_f32_e32 v0, 0, v0
	v_max_f32_e32 v1, 0, v1
	v_max_f32_e32 v2, 0, v2
	v_max_f32_e32 v3, 0, v3
	v_cvt_pk_bf16_f32 v208, v48, v49
	v_pk_mul_f32 v[48:49], v[50:51], v[50:51]
	v_max_f32_e32 v32, 0, v32
	v_max_f32_e32 v33, 0, v33
	v_max_f32_e32 v34, 0, v34
	v_max_f32_e32 v35, 0, v35
	v_max_f32_e32 v16, 0, v16
	v_max_f32_e32 v17, 0, v17
	v_max_f32_e32 v18, 0, v18
	v_max_f32_e32 v19, 0, v19
	v_pk_mul_f32 v[0:1], v[0:1], v[0:1]
	v_pk_mul_f32 v[2:3], v[2:3], v[2:3]
	v_cvt_pk_bf16_f32 v209, v48, v49
	v_lshl_add_u64 v[48:49], v[68:69], 0, v[66:67]
	v_pk_mul_f32 v[32:33], v[32:33], v[32:33]
	v_pk_mul_f32 v[34:35], v[34:35], v[34:35]
	v_pk_mul_f32 v[16:17], v[16:17], v[16:17]
	v_pk_mul_f32 v[18:19], v[18:19], v[18:19]
	v_cvt_pk_bf16_f32 v232, v0, v1
	v_cvt_pk_bf16_f32 v233, v2, v3
	v_accvgpr_read_b32 v20, a164
	v_accvgpr_read_b32 v21, a165
	v_accvgpr_read_b32 v22, a166
	v_accvgpr_read_b32 v23, a167
	v_cvt_pk_bf16_f32 v216, v32, v33
	v_cvt_pk_bf16_f32 v217, v34, v35
	v_cvt_pk_bf16_f32 v224, v16, v17
	v_cvt_pk_bf16_f32 v225, v18, v19
	v_mul_f32_e32 v0, v4, v65
	v_mul_f32_e32 v1, v5, v65
	v_mul_f32_e32 v2, v6, v65
	v_mul_f32_e32 v3, v7, v65
	v_mul_f32_e32 v50, v52, v65
	v_mul_f32_e32 v51, v53, v65
	v_mul_f32_e32 v52, v54, v65
	v_mul_f32_e32 v53, v55, v65
	v_mul_f32_e32 v32, v36, v65
	v_mul_f32_e32 v33, v37, v65
	v_mul_f32_e32 v34, v38, v65
	v_mul_f32_e32 v35, v39, v65
	v_mul_f32_e32 v16, v20, v65
	v_mul_f32_e32 v17, v21, v65
	v_mul_f32_e32 v18, v22, v65
	v_mul_f32_e32 v19, v23, v65
	v_max_f32_e32 v0, 0, v0
	v_max_f32_e32 v1, 0, v1
	v_max_f32_e32 v2, 0, v2
	v_max_f32_e32 v3, 0, v3
	v_max_f32_e32 v50, 0, v50
	v_max_f32_e32 v51, 0, v51
	v_max_f32_e32 v52, 0, v52
	v_max_f32_e32 v53, 0, v53
	v_max_f32_e32 v32, 0, v32
	v_max_f32_e32 v33, 0, v33
	v_max_f32_e32 v34, 0, v34
	v_max_f32_e32 v35, 0, v35
	v_max_f32_e32 v16, 0, v16
	v_max_f32_e32 v17, 0, v17
	v_max_f32_e32 v18, 0, v18
	v_max_f32_e32 v19, 0, v19
	v_pk_mul_f32 v[0:1], v[0:1], v[0:1]
	v_pk_mul_f32 v[2:3], v[2:3], v[2:3]
	v_pk_mul_f32 v[50:51], v[50:51], v[50:51]
	v_pk_mul_f32 v[52:53], v[52:53], v[52:53]
	v_pk_mul_f32 v[32:33], v[32:33], v[32:33]
	v_pk_mul_f32 v[34:35], v[34:35], v[34:35]
	v_pk_mul_f32 v[16:17], v[16:17], v[16:17]
	v_pk_mul_f32 v[18:19], v[18:19], v[18:19]
	v_cvt_pk_bf16_f32 v234, v0, v1
	v_cvt_pk_bf16_f32 v235, v2, v3
	v_accvgpr_read_b32 v24, a168
	v_accvgpr_read_b32 v25, a169
	v_accvgpr_read_b32 v26, a170
	v_accvgpr_read_b32 v27, a171
	v_cvt_pk_bf16_f32 v210, v50, v51
	v_cvt_pk_bf16_f32 v211, v52, v53
	v_cvt_pk_bf16_f32 v218, v32, v33
	v_cvt_pk_bf16_f32 v219, v34, v35
	v_cvt_pk_bf16_f32 v226, v16, v17
	v_cvt_pk_bf16_f32 v227, v18, v19
	s_nop 1
	v_permlane32_swap_b32_e32 v232, v234
	v_permlane32_swap_b32_e32 v233, v235
	v_lshl_add_u64 v[204:205], v[48:49], 0, v[206:207]
	global_store_dwordx4 v[204:205], v[232:235], off offset:192
	v_mul_f32_e32 v0, v8, v65
	v_mul_f32_e32 v1, v9, v65
	v_mul_f32_e32 v2, v10, v65
	v_mul_f32_e32 v3, v11, v65
	v_mul_f32_e32 v50, v56, v65
	v_mul_f32_e32 v51, v57, v65
	v_mul_f32_e32 v52, v58, v65
	v_mul_f32_e32 v53, v59, v65
	s_nop 1
	v_permlane32_swap_b32_e32 v216, v218
	v_permlane32_swap_b32_e32 v217, v219
	v_lshl_add_u64 v[204:205], v[48:49], 0, v[206:207]
	global_store_dwordx4 v[204:205], v[216:219], off offset:64
	v_mul_f32_e32 v32, v40, v65
	v_mul_f32_e32 v33, v41, v65
	v_mul_f32_e32 v34, v42, v65
	v_mul_f32_e32 v35, v43, v65
	s_nop 1
	v_permlane32_swap_b32_e32 v224, v226
	v_permlane32_swap_b32_e32 v225, v227
	v_lshl_add_u64 v[204:205], v[48:49], 0, v[206:207]
	global_store_dwordx4 v[204:205], v[224:227], off offset:128
	v_mul_f32_e32 v16, v24, v65
	v_mul_f32_e32 v17, v25, v65
	v_mul_f32_e32 v18, v26, v65
	v_mul_f32_e32 v19, v27, v65
	v_max_f32_e32 v0, 0, v0
	v_max_f32_e32 v1, 0, v1
	v_max_f32_e32 v2, 0, v2
	v_max_f32_e32 v3, 0, v3
	v_max_f32_e32 v50, 0, v50
	v_max_f32_e32 v51, 0, v51
	v_max_f32_e32 v52, 0, v52
	v_max_f32_e32 v53, 0, v53
	v_max_f32_e32 v32, 0, v32
	v_max_f32_e32 v33, 0, v33
	v_max_f32_e32 v34, 0, v34
	v_max_f32_e32 v35, 0, v35
	v_max_f32_e32 v16, 0, v16
	v_max_f32_e32 v17, 0, v17
	v_max_f32_e32 v18, 0, v18
	v_max_f32_e32 v19, 0, v19
	v_pk_mul_f32 v[0:1], v[0:1], v[0:1]
	v_pk_mul_f32 v[2:3], v[2:3], v[2:3]
	v_pk_mul_f32 v[50:51], v[50:51], v[50:51]
	v_pk_mul_f32 v[52:53], v[52:53], v[52:53]
	v_pk_mul_f32 v[32:33], v[32:33], v[32:33]
; DEV uint32_t pk2(float lo, float hi) { f32x2 v; v[0] = lo; v[1] = hi; bf16v2 b = __builtin_convertvector(v, bf16v2); return __builtin_bit_cast(uint32_t, b); }
; DEV float rscale_of(const float* ssq, int m) {
;   const f32x4 a = *(const f32x4*)(ssq + (size_t)m * NPART), b = *(const f32x4*)(ssq + (size_t)m * NPART + 4);
;   const float s = (a[0] + a[1]) + (a[2] + a[3]) + (b[0] + b[1]) + (b[2] + b[3]);
;   return rsqrtf(s * (1.f / DM) + EPS);
; }
; template <int EPI>
; DEV void gemm_tile(CParams& p, int layer, const bf16_t* __restrict__ A, int lda, const bf16_t* __restrict__ Bt, int K, int m0, int n0, int nt, char* lds, const int swave) {
;     ...
;       const float rs = rscale_of(ssq, mc);
;       bf16_t* urow = (bf16_t*)(ws + W_U) + (size_t)mc * DFF;
; #pragma unroll
;       for (int j = 0; j < 4; ++j)
; #pragma unroll
;         for (int g = 0; g < 4; ++g) {
;           const int n = n0 + wn * 128 + j * 32 + 8 * g + 4 * hh;
;           float v0 = fmaxf(acc[j][i][4 * g] * rs, 0.f), v1 = fmaxf(acc[j][i][4 * g + 1] * rs, 0.f), v2 = fmaxf(acc[j][i][4 * g + 2] * rs, 0.f), v3 = fmaxf(acc[j][i][4 * g + 3] * rs, 0.f);
;           u32x2 pk; pk[0] = pk2(v0 * v0, v1 * v1); pk[1] = pk2(v2 * v2, v3 * v3);
;           *(u32x2*)(urow + n) = pk;
	v_pk_mul_f32 v[34:35], v[34:35], v[34:35]
	v_pk_mul_f32 v[16:17], v[16:17], v[16:17]
	v_pk_mul_f32 v[18:19], v[18:19], v[18:19]
	v_cvt_pk_bf16_f32 v236, v0, v1
	v_cvt_pk_bf16_f32 v237, v2, v3
	v_accvgpr_read_b32 v28, a172
	v_accvgpr_read_b32 v29, a173
	v_accvgpr_read_b32 v30, a174
	v_accvgpr_read_b32 v31, a175
	v_cvt_pk_bf16_f32 v212, v50, v51
	v_cvt_pk_bf16_f32 v213, v52, v53
	v_cvt_pk_bf16_f32 v220, v32, v33
	v_cvt_pk_bf16_f32 v221, v34, v35
	v_cvt_pk_bf16_f32 v228, v16, v17
	v_cvt_pk_bf16_f32 v229, v18, v19
	v_mul_f32_e32 v0, v12, v65
	v_mul_f32_e32 v1, v13, v65
	v_mul_f32_e32 v2, v14, v65
	v_mul_f32_e32 v3, v15, v65
	v_mul_f32_e32 v50, v60, v65
	v_mul_f32_e32 v51, v61, v65
	v_mul_f32_e32 v52, v62, v65
	v_mul_f32_e32 v53, v63, v65
	v_mul_f32_e32 v32, v44, v65
	v_mul_f32_e32 v33, v45, v65
	v_mul_f32_e32 v34, v46, v65
	v_mul_f32_e32 v35, v47, v65
	v_mul_f32_e32 v16, v28, v65
	v_mul_f32_e32 v17, v29, v65
	v_mul_f32_e32 v18, v30, v65
	v_mul_f32_e32 v19, v31, v65
	v_max_f32_e32 v0, 0, v0
	v_max_f32_e32 v1, 0, v1
	v_max_f32_e32 v2, 0, v2
	v_max_f32_e32 v3, 0, v3
	v_max_f32_e32 v50, 0, v50
	v_max_f32_e32 v51, 0, v51
	v_max_f32_e32 v52, 0, v52
	v_max_f32_e32 v53, 0, v53
	v_max_f32_e32 v32, 0, v32
	v_max_f32_e32 v33, 0, v33
	v_max_f32_e32 v34, 0, v34
	v_max_f32_e32 v35, 0, v35
	v_max_f32_e32 v16, 0, v16
	v_max_f32_e32 v17, 0, v17
	v_max_f32_e32 v18, 0, v18
	v_max_f32_e32 v19, 0, v19
	v_pk_mul_f32 v[0:1], v[0:1], v[0:1]
	v_pk_mul_f32 v[2:3], v[2:3], v[2:3]
	v_or_b32_e32 v68, 64, v64
	v_pk_mul_f32 v[50:51], v[50:51], v[50:51]
	v_pk_mul_f32 v[52:53], v[52:53], v[52:53]
	v_pk_mul_f32 v[32:33], v[32:33], v[32:33]
	v_pk_mul_f32 v[34:35], v[34:35], v[34:35]
	v_pk_mul_f32 v[16:17], v[16:17], v[16:17]
	v_pk_mul_f32 v[18:19], v[18:19], v[18:19]
	v_cvt_pk_bf16_f32 v238, v0, v1
	v_cvt_pk_bf16_f32 v239, v2, v3
	v_ashrrev_i32_e32 v69, 31, v68
	v_cvt_pk_bf16_f32 v214, v50, v51
	v_cvt_pk_bf16_f32 v215, v52, v53
	v_cvt_pk_bf16_f32 v222, v32, v33
	v_cvt_pk_bf16_f32 v223, v34, v35
	v_cvt_pk_bf16_f32 v230, v16, v17
	v_cvt_pk_bf16_f32 v231, v18, v19
	s_nop 1
	v_permlane32_swap_b32_e32 v236, v238
	v_permlane32_swap_b32_e32 v237, v239
	v_lshl_add_u64 v[204:205], v[48:49], 0, v[206:207]
	global_store_dwordx4 v[204:205], v[236:239], off offset:224
	v_lshlrev_b64 v[0:1], 5, v[68:69]
	s_nop 1
	v_permlane32_swap_b32_e32 v208, v210
	v_permlane32_swap_b32_e32 v209, v211
	v_lshl_add_u64 v[204:205], v[48:49], 0, v[206:207]
	global_store_dwordx4 v[204:205], v[208:211], off
	s_nop 1
	v_permlane32_swap_b32_e32 v212, v214
	v_permlane32_swap_b32_e32 v213, v215
	v_lshl_add_u64 v[204:205], v[48:49], 0, v[206:207]
	global_store_dwordx4 v[204:205], v[212:215], off offset:32
	s_nop 1
	v_permlane32_swap_b32_e32 v220, v222
	v_permlane32_swap_b32_e32 v221, v223
	v_lshl_add_u64 v[204:205], v[48:49], 0, v[206:207]
	global_store_dwordx4 v[204:205], v[220:223], off offset:96
	s_nop 1
	v_permlane32_swap_b32_e32 v228, v230
	v_permlane32_swap_b32_e32 v229, v231
	v_lshl_add_u64 v[204:205], v[48:49], 0, v[206:207]
	global_store_dwordx4 v[204:205], v[228:231], off offset:160
	v_lshl_add_u64 v[0:1], s[4:5], 0, v[0:1]
	global_load_dwordx4 v[16:19], v[0:1], off
	global_load_dwordx4 v[20:23], v[0:1], off offset:16
	v_accvgpr_read_b32 v48, a64
	v_accvgpr_read_b32 v0, a112
	v_accvgpr_read_b32 v49, a65
	v_accvgpr_read_b32 v1, a113
	v_accvgpr_read_b32 v2, a114
	v_accvgpr_read_b32 v3, a115
	v_accvgpr_read_b32 v32, a80
	v_accvgpr_read_b32 v50, a66
	v_accvgpr_read_b32 v51, a67
	v_accvgpr_read_b32 v33, a81
	v_accvgpr_read_b32 v34, a82
	v_accvgpr_read_b32 v35, a83
	v_lshlrev_b64 v[68:69], 13, v[68:69]
	v_lshl_add_u64 v[68:69], s[6:7], 0, v[68:69]
	v_accvgpr_read_b32 v4, a116
	v_accvgpr_read_b32 v5, a117
	v_accvgpr_read_b32 v6, a118
	v_accvgpr_read_b32 v7, a119
	v_accvgpr_read_b32 v36, a84
	v_accvgpr_read_b32 v37, a85
	v_accvgpr_read_b32 v38, a86
	v_accvgpr_read_b32 v39, a87
	v_accvgpr_read_b32 v52, a68
	v_accvgpr_read_b32 v53, a69
	v_accvgpr_read_b32 v54, a70
	v_accvgpr_read_b32 v55, a71
	v_accvgpr_read_b32 v8, a120
	v_accvgpr_read_b32 v9, a121
	v_accvgpr_read_b32 v10, a122
	v_accvgpr_read_b32 v11, a123
	v_accvgpr_read_b32 v40, a88
	v_accvgpr_read_b32 v41, a89
	v_accvgpr_read_b32 v42, a90
	v_accvgpr_read_b32 v43, a91
	v_accvgpr_read_b32 v56, a72
	v_accvgpr_read_b32 v57, a73
	v_accvgpr_read_b32 v58, a74
	v_accvgpr_read_b32 v59, a75
	v_accvgpr_read_b32 v12, a124
	v_accvgpr_read_b32 v13, a125
	v_accvgpr_read_b32 v14, a126
	v_accvgpr_read_b32 v15, a127
	v_accvgpr_read_b32 v44, a92
	v_accvgpr_read_b32 v45, a93
	v_accvgpr_read_b32 v46, a94
	v_accvgpr_read_b32 v47, a95
	v_accvgpr_read_b32 v60, a76
	v_accvgpr_read_b32 v61, a77
	v_accvgpr_read_b32 v62, a78
	v_accvgpr_read_b32 v63, a79
	v_or_b32_e32 v64, 0x60, v64
	s_waitcnt vmcnt(1)
	v_mov_b32_e32 v24, v17
	v_mov_b32_e32 v25, v18
	v_mov_b32_e32 v17, v19
	v_pk_add_f32 v[16:17], v[24:25], v[16:17]
	s_waitcnt vmcnt(0)
; DEV uint32_t pk2(float lo, float hi) { f32x2 v; v[0] = lo; v[1] = hi; bf16v2 b = __builtin_convertvector(v, bf16v2); return __builtin_bit_cast(uint32_t, b); }
; DEV float rscale_of(const float* ssq, int m) {
;   const f32x4 a = *(const f32x4*)(ssq + (size_t)m * NPART), b = *(const f32x4*)(ssq + (size_t)m * NPART + 4);
;   const float s = (a[0] + a[1]) + (a[2] + a[3]) + (b[0] + b[1]) + (b[2] + b[3]);
;   return rsqrtf(s * (1.f / DM) + EPS);
; }
; template <int EPI>
; DEV void gemm_tile(CParams& p, int layer, const bf16_t* __restrict__ A, int lda, const bf16_t* __restrict__ Bt, int K, int m0, int n0, int nt, char* lds, const int swave) {
;     ...
;       const float rs = rscale_of(ssq, mc);
;       bf16_t* urow = (bf16_t*)(ws + W_U) + (size_t)mc * DFF;
; #pragma unroll
;       for (int j = 0; j < 4; ++j)
; #pragma unroll
;         for (int g = 0; g < 4; ++g) {
;           const int n = n0 + wn * 128 + j * 32 + 8 * g + 4 * hh;
;           float v0 = fmaxf(acc[j][i][4 * g] * rs, 0.f), v1 = fmaxf(acc[j][i][4 * g + 1] * rs, 0.f), v2 = fmaxf(acc[j][i][4 * g + 2] * rs, 0.f), v3 = fmaxf(acc[j][i][4 * g + 3] * rs, 0.f);
;           u32x2 pk; pk[0] = pk2(v0 * v0, v1 * v1); pk[1] = pk2(v2 * v2, v3 * v3);
;           *(u32x2*)(urow + n) = pk;
	v_mov_b32_e32 v18, v22
	v_mov_b32_e32 v19, v20
	v_mov_b32_e32 v20, v23
	v_pk_add_f32 v[18:19], v[18:19], v[20:21]
	v_add_f32_e32 v16, v16, v17
	v_add_f32_e32 v16, v16, v19
	v_add_f32_e32 v16, v18, v16
	v_fmamk_f32 v16, v16, 0x3a800000, v242
	v_mul_f32_e32 v17, 0x4b800000, v16
	v_cmp_gt_f32_e32 vcc, s25, v16
	s_nop 1
	v_cndmask_b32_e32 v16, v16, v17, vcc
	v_rsq_f32_e32 v65, v16
	v_accvgpr_read_b32 v16, a96
	v_accvgpr_read_b32 v17, a97
	v_accvgpr_read_b32 v18, a98
	v_mul_f32_e32 v70, 0x45800000, v65
	v_cndmask_b32_e32 v65, v65, v70, vcc
	v_mul_f32_e32 v48, v48, v65
	v_mul_f32_e32 v49, v49, v65
	v_accvgpr_read_b32 v19, a99
	v_max_f32_e32 v48, 0, v48
	v_max_f32_e32 v49, 0, v49
	v_mul_f32_e32 v50, v50, v65
	v_mul_f32_e32 v51, v51, v65
	v_mul_f32_e32 v0, v0, v65
	v_mul_f32_e32 v1, v1, v65
	v_mul_f32_e32 v2, v2, v65
	v_mul_f32_e32 v3, v3, v65
	v_max_f32_e32 v50, 0, v50
	v_max_f32_e32 v51, 0, v51
	v_pk_mul_f32 v[48:49], v[48:49], v[48:49]
	v_mul_f32_e32 v32, v32, v65
	v_mul_f32_e32 v33, v33, v65
	v_mul_f32_e32 v34, v34, v65
	v_mul_f32_e32 v35, v35, v65
	v_mul_f32_e32 v16, v16, v65
	v_mul_f32_e32 v17, v17, v65
	v_mul_f32_e32 v18, v18, v65
	v_mul_f32_e32 v19, v19, v65
	v_max_f32_e32 v0, 0, v0
	v_max_f32_e32 v1, 0, v1
	v_max_f32_e32 v2, 0, v2
	v_max_f32_e32 v3, 0, v3
	v_cvt_pk_bf16_f32 v208, v48, v49
	v_pk_mul_f32 v[48:49], v[50:51], v[50:51]
	v_max_f32_e32 v32, 0, v32
	v_max_f32_e32 v33, 0, v33
	v_max_f32_e32 v34, 0, v34
	v_max_f32_e32 v35, 0, v35
	v_max_f32_e32 v16, 0, v16
	v_max_f32_e32 v17, 0, v17
	v_max_f32_e32 v18, 0, v18
	v_max_f32_e32 v19, 0, v19
	v_pk_mul_f32 v[0:1], v[0:1], v[0:1]
	v_pk_mul_f32 v[2:3], v[2:3], v[2:3]
	v_cvt_pk_bf16_f32 v209, v48, v49
	v_lshl_add_u64 v[48:49], v[68:69], 0, v[66:67]
	v_pk_mul_f32 v[32:33], v[32:33], v[32:33]
	v_pk_mul_f32 v[34:35], v[34:35], v[34:35]
	v_pk_mul_f32 v[16:17], v[16:17], v[16:17]
	v_pk_mul_f32 v[18:19], v[18:19], v[18:19]
	v_cvt_pk_bf16_f32 v232, v0, v1
	v_cvt_pk_bf16_f32 v233, v2, v3
	v_accvgpr_read_b32 v20, a100
	v_accvgpr_read_b32 v21, a101
	v_accvgpr_read_b32 v22, a102
	v_accvgpr_read_b32 v23, a103
	v_cvt_pk_bf16_f32 v216, v32, v33
	v_cvt_pk_bf16_f32 v217, v34, v35
	v_cvt_pk_bf16_f32 v224, v16, v17
	v_cvt_pk_bf16_f32 v225, v18, v19
	v_mul_f32_e32 v0, v4, v65
	v_mul_f32_e32 v1, v5, v65
	v_mul_f32_e32 v2, v6, v65
	v_mul_f32_e32 v3, v7, v65
	v_mul_f32_e32 v50, v52, v65
	v_mul_f32_e32 v51, v53, v65
	v_mul_f32_e32 v52, v54, v65
	v_mul_f32_e32 v53, v55, v65
	v_mul_f32_e32 v32, v36, v65
	v_mul_f32_e32 v33, v37, v65
	v_mul_f32_e32 v34, v38, v65
	v_mul_f32_e32 v35, v39, v65
	v_mul_f32_e32 v16, v20, v65
	v_mul_f32_e32 v17, v21, v65
	v_mul_f32_e32 v18, v22, v65
	v_mul_f32_e32 v19, v23, v65
	v_max_f32_e32 v0, 0, v0
	v_max_f32_e32 v1, 0, v1
	v_max_f32_e32 v2, 0, v2
	v_max_f32_e32 v3, 0, v3
	v_max_f32_e32 v50, 0, v50
	v_max_f32_e32 v51, 0, v51
	v_max_f32_e32 v52, 0, v52
	v_max_f32_e32 v53, 0, v53
	v_max_f32_e32 v32, 0, v32
	v_max_f32_e32 v33, 0, v33
	v_max_f32_e32 v34, 0, v34
	v_max_f32_e32 v35, 0, v35
	v_max_f32_e32 v16, 0, v16
	v_max_f32_e32 v17, 0, v17
	v_max_f32_e32 v18, 0, v18
	v_max_f32_e32 v19, 0, v19
	v_pk_mul_f32 v[0:1], v[0:1], v[0:1]
	v_pk_mul_f32 v[2:3], v[2:3], v[2:3]
	v_pk_mul_f32 v[50:51], v[50:51], v[50:51]
	v_pk_mul_f32 v[52:53], v[52:53], v[52:53]
	v_pk_mul_f32 v[32:33], v[32:33], v[32:33]
	v_pk_mul_f32 v[34:35], v[34:35], v[34:35]
	v_pk_mul_f32 v[16:17], v[16:17], v[16:17]
	v_pk_mul_f32 v[18:19], v[18:19], v[18:19]
	v_cvt_pk_bf16_f32 v234, v0, v1
	v_cvt_pk_bf16_f32 v235, v2, v3
	v_accvgpr_read_b32 v24, a104
	v_accvgpr_read_b32 v25, a105
	v_accvgpr_read_b32 v26, a106
	v_accvgpr_read_b32 v27, a107
	v_cvt_pk_bf16_f32 v210, v50, v51
	v_cvt_pk_bf16_f32 v211, v52, v53
	v_cvt_pk_bf16_f32 v218, v32, v33
	v_cvt_pk_bf16_f32 v219, v34, v35
	v_cvt_pk_bf16_f32 v226, v16, v17
	v_cvt_pk_bf16_f32 v227, v18, v19
	s_nop 1
	v_permlane32_swap_b32_e32 v232, v234
	v_permlane32_swap_b32_e32 v233, v235
	v_lshl_add_u64 v[204:205], v[48:49], 0, v[206:207]
	global_store_dwordx4 v[204:205], v[232:235], off offset:192
	v_mul_f32_e32 v0, v8, v65
	v_mul_f32_e32 v1, v9, v65
	v_mul_f32_e32 v2, v10, v65
	v_mul_f32_e32 v3, v11, v65
	v_mul_f32_e32 v50, v56, v65
	v_mul_f32_e32 v51, v57, v65
	v_mul_f32_e32 v52, v58, v65
	v_mul_f32_e32 v53, v59, v65
	s_nop 1
	v_permlane32_swap_b32_e32 v216, v218
	v_permlane32_swap_b32_e32 v217, v219
	v_lshl_add_u64 v[204:205], v[48:49], 0, v[206:207]
	global_store_dwordx4 v[204:205], v[216:219], off offset:64
	v_mul_f32_e32 v32, v40, v65
	v_mul_f32_e32 v33, v41, v65
	v_mul_f32_e32 v34, v42, v65
	v_mul_f32_e32 v35, v43, v65
	s_nop 1
	v_permlane32_swap_b32_e32 v224, v226
	v_permlane32_swap_b32_e32 v225, v227
	v_lshl_add_u64 v[204:205], v[48:49], 0, v[206:207]
	global_store_dwordx4 v[204:205], v[224:227], off offset:128
	v_mul_f32_e32 v16, v24, v65
	v_mul_f32_e32 v17, v25, v65
	v_mul_f32_e32 v18, v26, v65
	v_mul_f32_e32 v19, v27, v65
	v_max_f32_e32 v0, 0, v0
	v_max_f32_e32 v1, 0, v1
	v_max_f32_e32 v2, 0, v2
	v_max_f32_e32 v3, 0, v3
	v_max_f32_e32 v50, 0, v50
	v_max_f32_e32 v51, 0, v51
	v_max_f32_e32 v52, 0, v52
	v_max_f32_e32 v53, 0, v53
	v_max_f32_e32 v32, 0, v32
	v_max_f32_e32 v33, 0, v33
	v_max_f32_e32 v34, 0, v34
	v_max_f32_e32 v35, 0, v35
	v_max_f32_e32 v16, 0, v16
	v_max_f32_e32 v17, 0, v17
	v_max_f32_e32 v18, 0, v18
	v_max_f32_e32 v19, 0, v19
	v_pk_mul_f32 v[0:1], v[0:1], v[0:1]
	v_pk_mul_f32 v[2:3], v[2:3], v[2:3]
	v_pk_mul_f32 v[50:51], v[50:51], v[50:51]
	v_pk_mul_f32 v[52:53], v[52:53], v[52:53]
	v_pk_mul_f32 v[32:33], v[32:33], v[32:33]
	v_pk_mul_f32 v[34:35], v[34:35], v[34:35]
	v_pk_mul_f32 v[16:17], v[16:17], v[16:17]
	v_pk_mul_f32 v[18:19], v[18:19], v[18:19]
; DEV uint32_t pk2(float lo, float hi) { f32x2 v; v[0] = lo; v[1] = hi; bf16v2 b = __builtin_convertvector(v, bf16v2); return __builtin_bit_cast(uint32_t, b); }
; DEV float rscale_of(const float* ssq, int m) {
;   const f32x4 a = *(const f32x4*)(ssq + (size_t)m * NPART), b = *(const f32x4*)(ssq + (size_t)m * NPART + 4);
;   const float s = (a[0] + a[1]) + (a[2] + a[3]) + (b[0] + b[1]) + (b[2] + b[3]);
;   return rsqrtf(s * (1.f / DM) + EPS);
; }
; template <int EPI>
; DEV void gemm_tile(CParams& p, int layer, const bf16_t* __restrict__ A, int lda, const bf16_t* __restrict__ Bt, int K, int m0, int n0, int nt, char* lds, const int swave) {
;     ...
;       const float rs = rscale_of(ssq, mc);
;       bf16_t* urow = (bf16_t*)(ws + W_U) + (size_t)mc * DFF;
; #pragma unroll
;       for (int j = 0; j < 4; ++j)
; #pragma unroll
;         for (int g = 0; g < 4; ++g) {
;           const int n = n0 + wn * 128 + j * 32 + 8 * g + 4 * hh;
;           float v0 = fmaxf(acc[j][i][4 * g] * rs, 0.f), v1 = fmaxf(acc[j][i][4 * g + 1] * rs, 0.f), v2 = fmaxf(acc[j][i][4 * g + 2] * rs, 0.f), v3 = fmaxf(acc[j][i][4 * g + 3] * rs, 0.f);
;           u32x2 pk; pk[0] = pk2(v0 * v0, v1 * v1); pk[1] = pk2(v2 * v2, v3 * v3);
;           *(u32x2*)(urow + n) = pk;
	v_cvt_pk_bf16_f32 v236, v0, v1
	v_cvt_pk_bf16_f32 v237, v2, v3
	v_accvgpr_read_b32 v28, a108
	v_accvgpr_read_b32 v29, a109
	v_accvgpr_read_b32 v30, a110
	v_accvgpr_read_b32 v31, a111
	v_cvt_pk_bf16_f32 v212, v50, v51
	v_cvt_pk_bf16_f32 v213, v52, v53
	v_cvt_pk_bf16_f32 v220, v32, v33
	v_cvt_pk_bf16_f32 v221, v34, v35
	v_cvt_pk_bf16_f32 v228, v16, v17
	v_cvt_pk_bf16_f32 v229, v18, v19
	v_mul_f32_e32 v0, v12, v65
	v_mul_f32_e32 v1, v13, v65
	v_mul_f32_e32 v2, v14, v65
	v_mul_f32_e32 v3, v15, v65
	v_mul_f32_e32 v50, v60, v65
	v_mul_f32_e32 v51, v61, v65
	v_mul_f32_e32 v52, v62, v65
	v_mul_f32_e32 v53, v63, v65
	v_mul_f32_e32 v32, v44, v65
	v_mul_f32_e32 v33, v45, v65
	v_mul_f32_e32 v34, v46, v65
	v_mul_f32_e32 v35, v47, v65
	v_mul_f32_e32 v16, v28, v65
	v_mul_f32_e32 v17, v29, v65
	v_mul_f32_e32 v18, v30, v65
	v_mul_f32_e32 v19, v31, v65
	v_max_f32_e32 v0, 0, v0
	v_max_f32_e32 v1, 0, v1
	v_max_f32_e32 v2, 0, v2
	v_max_f32_e32 v3, 0, v3
	v_max_f32_e32 v50, 0, v50
	v_max_f32_e32 v51, 0, v51
	v_max_f32_e32 v52, 0, v52
	v_max_f32_e32 v53, 0, v53
	v_max_f32_e32 v32, 0, v32
	v_max_f32_e32 v33, 0, v33
	v_max_f32_e32 v34, 0, v34
	v_max_f32_e32 v35, 0, v35
	v_max_f32_e32 v16, 0, v16
	v_max_f32_e32 v17, 0, v17
	v_max_f32_e32 v18, 0, v18
	v_max_f32_e32 v19, 0, v19
	v_pk_mul_f32 v[0:1], v[0:1], v[0:1]
	v_pk_mul_f32 v[2:3], v[2:3], v[2:3]
	v_pk_mul_f32 v[50:51], v[50:51], v[50:51]
	v_pk_mul_f32 v[52:53], v[52:53], v[52:53]
	v_pk_mul_f32 v[32:33], v[32:33], v[32:33]
	v_pk_mul_f32 v[34:35], v[34:35], v[34:35]
	v_pk_mul_f32 v[16:17], v[16:17], v[16:17]
	v_pk_mul_f32 v[18:19], v[18:19], v[18:19]
	v_cvt_pk_bf16_f32 v238, v0, v1
	v_cvt_pk_bf16_f32 v239, v2, v3
	v_ashrrev_i32_e32 v65, 31, v64
	v_cvt_pk_bf16_f32 v214, v50, v51
	v_cvt_pk_bf16_f32 v215, v52, v53
	v_cvt_pk_bf16_f32 v222, v32, v33
	v_cvt_pk_bf16_f32 v223, v34, v35
	v_cvt_pk_bf16_f32 v230, v16, v17
	v_cvt_pk_bf16_f32 v231, v18, v19
	s_nop 1
	v_permlane32_swap_b32_e32 v236, v238
	v_permlane32_swap_b32_e32 v237, v239
	v_lshl_add_u64 v[204:205], v[48:49], 0, v[206:207]
	global_store_dwordx4 v[204:205], v[236:239], off offset:224
	v_lshlrev_b64 v[0:1], 5, v[64:65]
	s_nop 1
	v_permlane32_swap_b32_e32 v208, v210
	v_permlane32_swap_b32_e32 v209, v211
	v_lshl_add_u64 v[204:205], v[48:49], 0, v[206:207]
	global_store_dwordx4 v[204:205], v[208:211], off
	s_nop 1
	v_permlane32_swap_b32_e32 v212, v214
	v_permlane32_swap_b32_e32 v213, v215
	v_lshl_add_u64 v[204:205], v[48:49], 0, v[206:207]
	global_store_dwordx4 v[204:205], v[212:215], off offset:32
	s_nop 1
	v_permlane32_swap_b32_e32 v220, v222
	v_permlane32_swap_b32_e32 v221, v223
	v_lshl_add_u64 v[204:205], v[48:49], 0, v[206:207]
	global_store_dwordx4 v[204:205], v[220:223], off offset:96
	s_nop 1
	v_permlane32_swap_b32_e32 v228, v230
	v_permlane32_swap_b32_e32 v229, v231
	v_lshl_add_u64 v[204:205], v[48:49], 0, v[206:207]
	global_store_dwordx4 v[204:205], v[228:231], off offset:160
	v_lshl_add_u64 v[0:1], s[4:5], 0, v[0:1]
	global_load_dwordx4 v[16:19], v[0:1], off
	global_load_dwordx4 v[20:23], v[0:1], off offset:16
	v_accvgpr_read_b32 v63, a15
	v_accvgpr_read_b32 v0, a48
	v_accvgpr_read_b32 v47, a31
	v_accvgpr_read_b32 v49, a1
	v_accvgpr_read_b32 v48, a0
	v_accvgpr_read_b32 v1, a49
	v_accvgpr_read_b32 v2, a50
	v_accvgpr_read_b32 v3, a51
	v_accvgpr_read_b32 v35, a19
	v_accvgpr_read_b32 v34, a18
	v_accvgpr_read_b32 v33, a17
	v_accvgpr_read_b32 v32, a16
	v_accvgpr_read_b32 v51, a3
	v_accvgpr_read_b32 v50, a2
	v_lshlrev_b64 v[64:65], 13, v[64:65]
	v_lshl_add_u64 v[64:65], s[6:7], 0, v[64:65]
	v_accvgpr_read_b32 v4, a52
	v_accvgpr_read_b32 v5, a53
	v_accvgpr_read_b32 v6, a54
	v_accvgpr_read_b32 v7, a55
	v_accvgpr_read_b32 v39, a23
	v_accvgpr_read_b32 v38, a22
	v_accvgpr_read_b32 v37, a21
	v_accvgpr_read_b32 v36, a20
	v_accvgpr_read_b32 v55, a7
	v_accvgpr_read_b32 v54, a6
	v_accvgpr_read_b32 v53, a5
	v_accvgpr_read_b32 v52, a4
	v_accvgpr_read_b32 v8, a56
	v_accvgpr_read_b32 v9, a57
	v_accvgpr_read_b32 v10, a58
	v_accvgpr_read_b32 v11, a59
	v_accvgpr_read_b32 v43, a27
	v_accvgpr_read_b32 v42, a26
	v_accvgpr_read_b32 v41, a25
	v_accvgpr_read_b32 v40, a24
	v_accvgpr_read_b32 v59, a11
	v_accvgpr_read_b32 v58, a10
	v_accvgpr_read_b32 v57, a9
	v_accvgpr_read_b32 v56, a8
	v_accvgpr_read_b32 v12, a60
	v_accvgpr_read_b32 v13, a61
	v_accvgpr_read_b32 v14, a62
	v_accvgpr_read_b32 v15, a63
	v_accvgpr_read_b32 v46, a30
	v_accvgpr_read_b32 v45, a29
	v_accvgpr_read_b32 v44, a28
	v_accvgpr_read_b32 v62, a14
	v_accvgpr_read_b32 v61, a13
	v_accvgpr_read_b32 v60, a12
	s_waitcnt vmcnt(1)
	v_mov_b32_e32 v24, v17
	v_mov_b32_e32 v25, v18
	v_mov_b32_e32 v17, v19
	v_pk_add_f32 v[16:17], v[24:25], v[16:17]
	s_waitcnt vmcnt(0)
; DEV uint32_t pk2(float lo, float hi) { f32x2 v; v[0] = lo; v[1] = hi; bf16v2 b = __builtin_convertvector(v, bf16v2); return __builtin_bit_cast(uint32_t, b); }
; DEV float rscale_of(const float* ssq, int m) {
;   const f32x4 a = *(const f32x4*)(ssq + (size_t)m * NPART), b = *(const f32x4*)(ssq + (size_t)m * NPART + 4);
;   const float s = (a[0] + a[1]) + (a[2] + a[3]) + (b[0] + b[1]) + (b[2] + b[3]);
;   return rsqrtf(s * (1.f / DM) + EPS);
; }
; template <int EPI>
; DEV void gemm_tile(CParams& p, int layer, const bf16_t* __restrict__ A, int lda, const bf16_t* __restrict__ Bt, int K, int m0, int n0, int nt, char* lds, const int swave) {
;     ...
;       const float rs = rscale_of(ssq, mc);
;       bf16_t* urow = (bf16_t*)(ws + W_U) + (size_t)mc * DFF;
; #pragma unroll
;       for (int j = 0; j < 4; ++j)
; #pragma unroll
;         for (int g = 0; g < 4; ++g) {
;           const int n = n0 + wn * 128 + j * 32 + 8 * g + 4 * hh;
;           float v0 = fmaxf(acc[j][i][4 * g] * rs, 0.f), v1 = fmaxf(acc[j][i][4 * g + 1] * rs, 0.f), v2 = fmaxf(acc[j][i][4 * g + 2] * rs, 0.f), v3 = fmaxf(acc[j][i][4 * g + 3] * rs, 0.f);
;           u32x2 pk; pk[0] = pk2(v0 * v0, v1 * v1); pk[1] = pk2(v2 * v2, v3 * v3);
;           *(u32x2*)(urow + n) = pk;
	v_mov_b32_e32 v18, v22
	v_mov_b32_e32 v19, v20
	v_mov_b32_e32 v20, v23
	v_pk_add_f32 v[18:19], v[18:19], v[20:21]
	v_add_f32_e32 v16, v16, v17
	v_add_f32_e32 v16, v16, v19
	v_add_f32_e32 v16, v18, v16
	v_fmamk_f32 v16, v16, 0x3a800000, v242
	v_mul_f32_e32 v17, 0x4b800000, v16
	v_cmp_gt_f32_e32 vcc, s25, v16
	s_nop 1
	v_cndmask_b32_e32 v16, v16, v17, vcc
	v_rsq_f32_e32 v68, v16
	v_accvgpr_read_b32 v16, a32
	v_accvgpr_read_b32 v17, a33
	v_accvgpr_read_b32 v18, a34
	v_mul_f32_e32 v69, 0x45800000, v68
	v_cndmask_b32_e32 v70, v68, v69, vcc
	v_accvgpr_read_b32 v19, a35
	v_mul_f32_e32 v48, v48, v70
	v_mul_f32_e32 v49, v49, v70
	v_max_f32_e32 v48, 0, v48
	v_max_f32_e32 v49, 0, v49
	v_mul_f32_e32 v50, v50, v70
	v_mul_f32_e32 v51, v51, v70
	v_mul_f32_e32 v32, v32, v70
	v_mul_f32_e32 v33, v33, v70
	v_mul_f32_e32 v34, v34, v70
	v_mul_f32_e32 v35, v35, v70
	v_mul_f32_e32 v16, v16, v70
	v_mul_f32_e32 v17, v17, v70
	v_mul_f32_e32 v18, v18, v70
	v_mul_f32_e32 v19, v19, v70
	v_mul_f32_e32 v0, v0, v70
	v_mul_f32_e32 v1, v1, v70
	v_mul_f32_e32 v2, v2, v70
	v_mul_f32_e32 v3, v3, v70
	v_max_f32_e32 v50, 0, v50
	v_max_f32_e32 v51, 0, v51
	v_pk_mul_f32 v[48:49], v[48:49], v[48:49]
	v_max_f32_e32 v32, 0, v32
	v_max_f32_e32 v33, 0, v33
	v_max_f32_e32 v34, 0, v34
	v_max_f32_e32 v35, 0, v35
	v_max_f32_e32 v16, 0, v16
	v_max_f32_e32 v17, 0, v17
	v_max_f32_e32 v18, 0, v18
	v_max_f32_e32 v19, 0, v19
	v_max_f32_e32 v0, 0, v0
	v_max_f32_e32 v1, 0, v1
	v_max_f32_e32 v2, 0, v2
	v_max_f32_e32 v3, 0, v3
	v_cvt_pk_bf16_f32 v208, v48, v49
	v_pk_mul_f32 v[48:49], v[50:51], v[50:51]
	v_pk_mul_f32 v[32:33], v[32:33], v[32:33]
	v_pk_mul_f32 v[34:35], v[34:35], v[34:35]
	v_pk_mul_f32 v[16:17], v[16:17], v[16:17]
	v_pk_mul_f32 v[18:19], v[18:19], v[18:19]
	v_pk_mul_f32 v[0:1], v[0:1], v[0:1]
	v_pk_mul_f32 v[2:3], v[2:3], v[2:3]
	v_accvgpr_read_b32 v20, a36
	v_accvgpr_read_b32 v21, a37
	v_accvgpr_read_b32 v22, a38
	v_accvgpr_read_b32 v23, a39
	v_cvt_pk_bf16_f32 v209, v48, v49
	v_lshl_add_u64 v[48:49], v[64:65], 0, v[66:67]
	v_cvt_pk_bf16_f32 v216, v32, v33
	v_cvt_pk_bf16_f32 v217, v34, v35
	v_cvt_pk_bf16_f32 v224, v16, v17
	v_cvt_pk_bf16_f32 v225, v18, v19
	v_cvt_pk_bf16_f32 v232, v0, v1
	v_cvt_pk_bf16_f32 v233, v2, v3
	v_mul_f32_e32 v50, v52, v70
	v_mul_f32_e32 v51, v53, v70
	v_mul_f32_e32 v52, v54, v70
	v_mul_f32_e32 v53, v55, v70
	v_mul_f32_e32 v32, v36, v70
	v_mul_f32_e32 v33, v37, v70
	v_mul_f32_e32 v34, v38, v70
	v_mul_f32_e32 v35, v39, v70
	v_mul_f32_e32 v16, v20, v70
	v_mul_f32_e32 v17, v21, v70
	v_mul_f32_e32 v18, v22, v70
	v_mul_f32_e32 v19, v23, v70
	v_mul_f32_e32 v0, v4, v70
	v_mul_f32_e32 v1, v5, v70
	v_mul_f32_e32 v2, v6, v70
	v_mul_f32_e32 v3, v7, v70
	v_max_f32_e32 v50, 0, v50
	v_max_f32_e32 v51, 0, v51
	v_max_f32_e32 v52, 0, v52
	v_max_f32_e32 v53, 0, v53
	v_max_f32_e32 v32, 0, v32
	v_max_f32_e32 v33, 0, v33
	v_max_f32_e32 v34, 0, v34
	v_max_f32_e32 v35, 0, v35
	v_max_f32_e32 v16, 0, v16
	v_max_f32_e32 v17, 0, v17
	v_max_f32_e32 v18, 0, v18
	v_max_f32_e32 v19, 0, v19
	v_max_f32_e32 v0, 0, v0
	v_max_f32_e32 v1, 0, v1
	v_max_f32_e32 v2, 0, v2
	v_max_f32_e32 v3, 0, v3
	v_pk_mul_f32 v[50:51], v[50:51], v[50:51]
	v_pk_mul_f32 v[52:53], v[52:53], v[52:53]
	v_pk_mul_f32 v[32:33], v[32:33], v[32:33]
	v_pk_mul_f32 v[34:35], v[34:35], v[34:35]
	v_pk_mul_f32 v[16:17], v[16:17], v[16:17]
	v_pk_mul_f32 v[18:19], v[18:19], v[18:19]
	v_pk_mul_f32 v[0:1], v[0:1], v[0:1]
	v_pk_mul_f32 v[2:3], v[2:3], v[2:3]
	v_accvgpr_read_b32 v24, a40
	v_accvgpr_read_b32 v25, a41
	v_accvgpr_read_b32 v26, a42
	v_accvgpr_read_b32 v27, a43
	v_cvt_pk_bf16_f32 v210, v50, v51
	v_cvt_pk_bf16_f32 v211, v52, v53
	v_cvt_pk_bf16_f32 v218, v32, v33
	v_cvt_pk_bf16_f32 v219, v34, v35
	v_cvt_pk_bf16_f32 v226, v16, v17
	v_cvt_pk_bf16_f32 v227, v18, v19
	v_cvt_pk_bf16_f32 v234, v0, v1
	v_cvt_pk_bf16_f32 v235, v2, v3
	v_mul_f32_e32 v50, v56, v70
	v_mul_f32_e32 v51, v57, v70
	v_mul_f32_e32 v52, v58, v70
	v_mul_f32_e32 v53, v59, v70
	s_nop 1
	v_permlane32_swap_b32_e32 v216, v218
	v_permlane32_swap_b32_e32 v217, v219
	v_lshl_add_u64 v[204:205], v[48:49], 0, v[206:207]
	global_store_dwordx4 v[204:205], v[216:219], off offset:64
	v_mul_f32_e32 v32, v40, v70
	v_mul_f32_e32 v33, v41, v70
	v_mul_f32_e32 v34, v42, v70
	v_mul_f32_e32 v35, v43, v70
; DEV uint32_t pk2(float lo, float hi) { f32x2 v; v[0] = lo; v[1] = hi; bf16v2 b = __builtin_convertvector(v, bf16v2); return __builtin_bit_cast(uint32_t, b); }
; template <int EPI>
; DEV void gemm_tile(CParams& p, int layer, const bf16_t* __restrict__ A, int lda, const bf16_t* __restrict__ Bt, int K, int m0, int n0, int nt, char* lds, const int swave) {
;     ...
;       const float rs = rscale_of(ssq, mc);
;       bf16_t* urow = (bf16_t*)(ws + W_U) + (size_t)mc * DFF;
; #pragma unroll
;       for (int j = 0; j < 4; ++j)
; #pragma unroll
;         for (int g = 0; g < 4; ++g) {
;           const int n = n0 + wn * 128 + j * 32 + 8 * g + 4 * hh;
;           float v0 = fmaxf(acc[j][i][4 * g] * rs, 0.f), v1 = fmaxf(acc[j][i][4 * g + 1] * rs, 0.f), v2 = fmaxf(acc[j][i][4 * g + 2] * rs, 0.f), v3 = fmaxf(acc[j][i][4 * g + 3] * rs, 0.f);
;           u32x2 pk; pk[0] = pk2(v0 * v0, v1 * v1); pk[1] = pk2(v2 * v2, v3 * v3);
;           *(u32x2*)(urow + n) = pk;
	s_nop 1
	v_permlane32_swap_b32_e32 v224, v226
	v_permlane32_swap_b32_e32 v225, v227
	v_lshl_add_u64 v[204:205], v[48:49], 0, v[206:207]
	global_store_dwordx4 v[204:205], v[224:227], off offset:128
	v_mul_f32_e32 v16, v24, v70
	v_mul_f32_e32 v17, v25, v70
	v_mul_f32_e32 v18, v26, v70
	v_mul_f32_e32 v19, v27, v70
	s_nop 1
	v_permlane32_swap_b32_e32 v232, v234
	v_permlane32_swap_b32_e32 v233, v235
	v_lshl_add_u64 v[204:205], v[48:49], 0, v[206:207]
	global_store_dwordx4 v[204:205], v[232:235], off offset:192
	v_mul_f32_e32 v0, v8, v70
	v_mul_f32_e32 v1, v9, v70
	v_mul_f32_e32 v2, v10, v70
	v_mul_f32_e32 v3, v11, v70
	v_max_f32_e32 v50, 0, v50
	v_max_f32_e32 v51, 0, v51
	v_max_f32_e32 v52, 0, v52
	v_max_f32_e32 v53, 0, v53
	v_max_f32_e32 v32, 0, v32
	v_max_f32_e32 v33, 0, v33
	v_max_f32_e32 v34, 0, v34
	v_max_f32_e32 v35, 0, v35
	v_max_f32_e32 v16, 0, v16
	v_max_f32_e32 v17, 0, v17
	v_max_f32_e32 v18, 0, v18
	v_max_f32_e32 v19, 0, v19
	v_max_f32_e32 v0, 0, v0
	v_max_f32_e32 v1, 0, v1
	v_max_f32_e32 v2, 0, v2
	v_max_f32_e32 v3, 0, v3
	v_pk_mul_f32 v[50:51], v[50:51], v[50:51]
	v_pk_mul_f32 v[52:53], v[52:53], v[52:53]
	v_pk_mul_f32 v[32:33], v[32:33], v[32:33]
	v_pk_mul_f32 v[34:35], v[34:35], v[34:35]
	v_pk_mul_f32 v[16:17], v[16:17], v[16:17]
	v_pk_mul_f32 v[18:19], v[18:19], v[18:19]
	v_pk_mul_f32 v[0:1], v[0:1], v[0:1]
	v_pk_mul_f32 v[2:3], v[2:3], v[2:3]
	v_accvgpr_read_b32 v28, a44
	v_accvgpr_read_b32 v29, a45
	v_accvgpr_read_b32 v30, a46
	v_accvgpr_read_b32 v31, a47
	v_cvt_pk_bf16_f32 v212, v50, v51
	v_cvt_pk_bf16_f32 v213, v52, v53
	v_cvt_pk_bf16_f32 v220, v32, v33
	v_cvt_pk_bf16_f32 v221, v34, v35
	v_cvt_pk_bf16_f32 v228, v16, v17
	v_cvt_pk_bf16_f32 v229, v18, v19
	v_cvt_pk_bf16_f32 v236, v0, v1
	v_cvt_pk_bf16_f32 v237, v2, v3
	v_mul_f32_e32 v50, v60, v70
	v_mul_f32_e32 v51, v61, v70
	v_mul_f32_e32 v52, v62, v70
	v_mul_f32_e32 v53, v63, v70
	v_mul_f32_e32 v32, v44, v70
	v_mul_f32_e32 v33, v45, v70
	v_mul_f32_e32 v34, v46, v70
	v_mul_f32_e32 v35, v47, v70
	v_mul_f32_e32 v16, v28, v70
	v_mul_f32_e32 v17, v29, v70
	v_mul_f32_e32 v18, v30, v70
	v_mul_f32_e32 v19, v31, v70
	v_mul_f32_e32 v0, v12, v70
	v_mul_f32_e32 v1, v13, v70
	v_mul_f32_e32 v2, v14, v70
	v_mul_f32_e32 v3, v15, v70
	v_max_f32_e32 v50, 0, v50
	v_max_f32_e32 v51, 0, v51
	v_max_f32_e32 v52, 0, v52
	v_max_f32_e32 v53, 0, v53
	v_max_f32_e32 v32, 0, v32
	v_max_f32_e32 v33, 0, v33
	v_max_f32_e32 v34, 0, v34
	v_max_f32_e32 v35, 0, v35
	v_max_f32_e32 v16, 0, v16
	v_max_f32_e32 v17, 0, v17
	v_max_f32_e32 v18, 0, v18
	v_max_f32_e32 v19, 0, v19
	v_max_f32_e32 v0, 0, v0
	v_max_f32_e32 v1, 0, v1
	v_max_f32_e32 v2, 0, v2
	v_max_f32_e32 v3, 0, v3
	v_pk_mul_f32 v[50:51], v[50:51], v[50:51]
	v_pk_mul_f32 v[52:53], v[52:53], v[52:53]
	v_pk_mul_f32 v[32:33], v[32:33], v[32:33]
	v_pk_mul_f32 v[34:35], v[34:35], v[34:35]
	v_pk_mul_f32 v[16:17], v[16:17], v[16:17]
	v_pk_mul_f32 v[18:19], v[18:19], v[18:19]
	v_pk_mul_f32 v[0:1], v[0:1], v[0:1]
	v_pk_mul_f32 v[2:3], v[2:3], v[2:3]
	v_cvt_pk_bf16_f32 v214, v50, v51
	v_cvt_pk_bf16_f32 v215, v52, v53
	v_cvt_pk_bf16_f32 v222, v32, v33
	v_cvt_pk_bf16_f32 v223, v34, v35
	v_cvt_pk_bf16_f32 v230, v16, v17
	v_cvt_pk_bf16_f32 v231, v18, v19
	v_cvt_pk_bf16_f32 v238, v0, v1
	v_cvt_pk_bf16_f32 v239, v2, v3
	s_nop 1
	v_permlane32_swap_b32_e32 v208, v210
	v_permlane32_swap_b32_e32 v209, v211
	v_lshl_add_u64 v[204:205], v[48:49], 0, v[206:207]
	global_store_dwordx4 v[204:205], v[208:211], off
	s_nop 1
	v_permlane32_swap_b32_e32 v212, v214
	v_permlane32_swap_b32_e32 v213, v215
	v_lshl_add_u64 v[204:205], v[48:49], 0, v[206:207]
	global_store_dwordx4 v[204:205], v[212:215], off offset:32
	s_nop 1
	v_permlane32_swap_b32_e32 v220, v222
	v_permlane32_swap_b32_e32 v221, v223
	v_lshl_add_u64 v[204:205], v[48:49], 0, v[206:207]
	global_store_dwordx4 v[204:205], v[220:223], off offset:96
	s_nop 1
	v_permlane32_swap_b32_e32 v228, v230
	v_permlane32_swap_b32_e32 v229, v231
	v_lshl_add_u64 v[204:205], v[48:49], 0, v[206:207]
	global_store_dwordx4 v[204:205], v[228:231], off offset:160
	s_nop 1
	v_permlane32_swap_b32_e32 v236, v238
	v_permlane32_swap_b32_e32 v237, v239
	v_lshl_add_u64 v[204:205], v[48:49], 0, v[206:207]
	global_store_dwordx4 v[204:205], v[236:239], off offset:224
	s_cbranch_scc1 .LBB0_137

; DEV uint32_t pk2(float lo, float hi) { f32x2 v; v[0] = lo; v[1] = hi; bf16v2 b = __builtin_convertvector(v, bf16v2); return __builtin_bit_cast(uint32_t, b); }
; DEV f32x16 mfma32(bf16x8 a, bf16x8 b, f32x16 c) { return __builtin_amdgcn_mfma_f32_32x32x16_bf16(a, b, c, 0, 0, 0); }
; template <bool SAMPLE>
; DEV void attn_unit(CParams& p, int layer, int unit, float lam, float lam_init, char* lds, const int swave) {
;     ...
;   for (int t = 0; t < ntiles; ++t) {
;     const int tn = SAMPLE ? t + 1 : (t + 1 < ntiles ? t + 1 : t);
;     if (!SAMPLE || t + 1 < ntiles) gloadK(tn);
;     if (t < my_tiles) {
;       const char* Ks = lds + (t & 1) * A_BUF; const char* Vs = Ks + A_KT;
;       bf16x8 pf[2][4];
;       f32x16 S0, S1;
;       auto qk = [&](int br) {
;         const f32x16 zc = {0.f, 0.f, 0.f, 0.f, 0.f, 0.f, 0.f, 0.f, 0.f, 0.f, 0.f, 0.f, 0.f, 0.f, 0.f, 0.f};
; #pragma unroll
;         for (int ks = 0; ks < 4; ++ks) {
;           const bf16x8 k0 = lds_read8(Ks + lr * AK_B + (br * 64 + ks * 16 + hh * 8) * 2);
;           const bf16x8 k1 = lds_read8(Ks + (32 + lr) * AK_B + (br * 64 + ks * 16 + hh * 8) * 2);
;           S0 = mfma32(k0, qf[br][ks], ks == 0 ? zc : S0); S1 = mfma32(k1, qf[br][ks], ks == 0 ? zc : S1);
;         }
;         if (sample && t == 32) {
; #pragma unroll
;           for (int r = 0; r < 16; ++r) { if (r >= 8) S0[r] = -1e30f; S1[r] = -1e30f; }
;         }
;       };
;       auto sm8 = [&](const f32x16& Sx, int r0, float nm, float& lsum) -> bf16x8 {
;         f32x2 c2; c2[0] = cexp; c2[1] = cexp;
;         f32x2 nm2; nm2[0] = nm; nm2[1] = nm;
;         union { u32x4 u; bf16x8 b; } x;
;         f32x2 sum2; sum2[0] = 0.f; sum2[1] = 0.f;
; #pragma unroll
;         for (int r = 0; r < 8; r += 2) {
;           f32x2 v; v[0] = Sx[r0 + r]; v[1] = Sx[r0 + r + 1];
;           v = v * c2 + nm2;
;           f32x2 ex; ex[0] = __builtin_amdgcn_exp2f(v[0]); ex[1] = __builtin_amdgcn_exp2f(v[1]);
;           sum2 += ex;
;           x.u[r >> 1] = pk2(ex[0], ex[1]);
;         }
;         lsum += sum2[0] + sum2[1];
;         return x.b;
;       };
;       qk(0);
;       pf[0][0] = sm8(S0, 0, nmc[0], ls[0]); pf[0][1] = sm8(S0, 8, nmc[0], ls[0]);
;       pf[0][2] = sm8(S1, 0, nmc[0], ls[0]); pf[0][3] = sm8(S1, 8, nmc[0], ls[0]);
;       qk(1);
;       if (!SAMPLE || t + 1 < ntiles) gloadV(tn);
.LBB0_243:
	s_add_i32 s36, s37, 1
	s_cmp_ge_u32 s36, s23
	s_cselect_b64 s[6:7], -1, 0
	s_cmp_lt_u32 s36, s23
	s_cselect_b32 s8, s36, s37
	s_lshl_b32 s38, s8, 6
	s_add_i32 s8, s38, s28
	s_mul_hi_i32 s9, s8, 0xc00
	s_mulk_i32 s8, 0xc00
	s_or_b64 s[8:9], s[8:9], s[2:3]
	v_lshl_add_u64 v[54:55], s[8:9], 1, v[50:51]
	s_add_i32 s8, s30, s38
	s_mul_hi_i32 s9, s8, 0xc00
	s_mulk_i32 s8, 0xc00
	s_or_b64 s[8:9], s[8:9], s[2:3]
	v_lshl_add_u64 v[56:57], s[8:9], 1, v[50:51]
	s_add_i32 s8, s31, s38
	s_mul_hi_i32 s9, s8, 0xc00
	s_mulk_i32 s8, 0xc00
	s_or_b64 s[8:9], s[8:9], s[2:3]
	v_lshl_add_u64 v[58:59], s[8:9], 1, v[50:51]
	s_add_i32 s8, s34, s38
	s_mul_hi_i32 s9, s8, 0xc00
	s_mulk_i32 s8, 0xc00
	s_or_b64 s[8:9], s[8:9], s[2:3]
	global_load_dwordx4 v[4:7], v[54:55], off
	global_load_dwordx4 v[0:3], v[56:57], off
	v_lshl_add_u64 v[60:61], s[8:9], 1, v[50:51]
	global_load_dwordx4 v[12:15], v[58:59], off
	global_load_dwordx4 v[8:11], v[60:61], off
	global_load_dwordx4 v[194:197], v[54:55], off offset:1024
	global_load_dwordx4 v[198:201], v[56:57], off offset:1024
	global_load_dwordx4 v[202:205], v[58:59], off offset:1024
	global_load_dwordx4 v[206:209], v[60:61], off offset:1024
	s_cmp_ge_u32 s37, s29
	s_cselect_b64 s[8:9], -1, 0
	s_and_b64 vcc, exec, s[8:9]
	s_cbranch_vccnz .LBB0_245
	s_bitcmp1_b32 s37, 0
	s_cselect_b32 s38, 0x9400, 0
	s_add_i32 s38, s38, 16
	v_add3_u32 v118, s38, v85, v240
	ds_read_b128 v[62:65], v118
	ds_read_b128 v[66:69], v118 offset:32
	s_waitcnt lgkmcnt(1)
	v_mfma_f32_32x32x16_bf16 v[178:193], v[62:65], v[16:19], 0
	ds_read_b128 v[62:65], v118 offset:8704
	ds_read_b128 v[70:73], v118 offset:8736
	s_waitcnt lgkmcnt(1)
	v_mfma_f32_32x32x16_bf16 v[210:225], v[62:65], v[16:19], 0
	v_mfma_f32_32x32x16_bf16 v[178:193], v[66:69], v[20:23], v[178:193]
	ds_read_b128 v[62:65], v118 offset:64
	ds_read_b128 v[66:69], v118 offset:96
	s_waitcnt lgkmcnt(2)
	v_mfma_f32_32x32x16_bf16 v[210:225], v[70:73], v[20:23], v[210:225]
	s_waitcnt lgkmcnt(1)
	v_mfma_f32_32x32x16_bf16 v[178:193], v[62:65], v[24:27], v[178:193]
	ds_read_b128 v[62:65], v118 offset:8768
	ds_read_b128 v[70:73], v118 offset:8800
	ds_read_b128 v[88:91], v118 offset:128
	s_waitcnt lgkmcnt(2)
	v_mfma_f32_32x32x16_bf16 v[210:225], v[62:65], v[24:27], v[210:225]
	s_waitcnt lgkmcnt(0)
	v_mfma_f32_32x32x16_bf16 a[144:159], v[88:91], v[32:35], 0
	v_mfma_f32_32x32x16_bf16 v[178:193], v[66:69], v[28:31], v[178:193]
	v_mfma_f32_32x32x16_bf16 v[210:225], v[70:73], v[28:31], v[210:225]
	ds_read_b128 v[68:71], v118 offset:8832
	ds_read_b128 v[92:95], v118 offset:160
	ds_read_b128 v[88:91], v118 offset:8864
	s_nop 7
	v_fma_f32 v102, v180, s52, v48
	v_fma_f32 v103, v181, s52, v49
	s_waitcnt lgkmcnt(2)
	v_mfma_f32_32x32x16_bf16 a[128:143], v[68:71], v[32:35], 0
	v_fma_f32 v62, v184, s52, v48
	v_fma_f32 v63, v185, s52, v49
	s_waitcnt lgkmcnt(1)
	v_mfma_f32_32x32x16_bf16 a[144:159], v[92:95], v[36:39], a[144:159]
	ds_read_b128 v[92:95], v118 offset:192
	v_fma_f32 v66, v190, s52, v48
	v_fma_f32 v67, v191, s52, v49
	v_exp_f32_e32 v66, v66
	s_waitcnt lgkmcnt(1)
	v_mfma_f32_32x32x16_bf16 a[128:143], v[88:91], v[36:39], a[128:143]
	v_fma_f32 v88, v178, s52, v48
	v_fma_f32 v89, v179, s52, v49
	v_exp_f32_e32 v67, v67
	v_exp_f32_e32 v100, v88
	v_exp_f32_e32 v101, v89
	ds_read_b128 v[88:91], v118 offset:8896
	ds_read_b128 v[96:99], v118 offset:224
	s_waitcnt lgkmcnt(2)
	v_mfma_f32_32x32x16_bf16 a[144:159], v[92:95], v[40:43], a[144:159]
	v_exp_f32_e32 v94, v102
	v_exp_f32_e32 v95, v103
	v_cvt_pk_bf16_f32 v92, v100, v101
	v_add_f32_e32 v116, v94, v100
	v_add_f32_e32 v117, v95, v101
	ds_read_b128 v[100:103], v118 offset:8928
	s_waitcnt lgkmcnt(2)
	v_mfma_f32_32x32x16_bf16 a[128:143], v[88:91], v[40:43], a[128:143]
	v_fma_f32 v88, v182, s52, v48
	v_fma_f32 v89, v183, s52, v49
	v_exp_f32_e32 v90, v62
	v_exp_f32_e32 v88, v88
	v_exp_f32_e32 v89, v89
	v_exp_f32_e32 v91, v63
	v_add3_u32 v108, s38, v87, v86
	v_cvt_pk_bf16_f32 v93, v94, v95
	v_add_f32_e32 v62, v88, v116
	v_add_f32_e32 v63, v89, v117
	v_cvt_pk_bf16_f32 v94, v88, v89
	ds_read_b64_tr_b16 v[116:117], v108 offset:17408
	ds_read_b64_tr_b16 v[118:119], v108 offset:19968
	s_waitcnt lgkmcnt(2)
	v_mfma_f32_32x32x16_bf16 a[128:143], v[100:103], v[44:47], a[128:143]
	v_fma_f32 v88, v186, s52, v48
	v_fma_f32 v89, v187, s52, v49
	ds_read_b64_tr_b16 v[100:101], v108 offset:17472
	ds_read_b64_tr_b16 v[122:123], v108 offset:17536
	ds_read_b64_tr_b16 v[142:143], v108 offset:17600
	ds_read_b64_tr_b16 v[102:103], v108 offset:20032
	ds_read_b64_tr_b16 v[124:125], v108 offset:20096
	ds_read_b64_tr_b16 v[144:145], v108 offset:20160
	v_add_f32_e32 v62, v90, v62
	v_add_f32_e32 v63, v91, v63
	v_cvt_pk_bf16_f32 v95, v90, v91
	v_exp_f32_e32 v88, v88
	v_exp_f32_e32 v89, v89
	v_fma_f32 v90, v188, s52, v48
	v_fma_f32 v91, v189, s52, v49
	v_mfma_f32_32x32x16_bf16 a[144:159], v[96:99], v[44:47], a[144:159]
	v_exp_f32_e32 v90, v90
	v_exp_f32_e32 v91, v91
	v_add_f32_e64 v96, v88, 0
	v_fma_f32 v64, v192, s52, v48
	v_fma_f32 v65, v193, s52, v49
	v_cvt_pk_bf16_f32 v88, v88, v89
	v_add_f32_e32 v96, v90, v96
	v_add_f32_e32 v97, v91, v89
	v_exp_f32_e32 v98, v64
	s_waitcnt lgkmcnt(6)
	v_mfma_f32_32x32x16_bf16 a[0:15], v[116:119], v[92:95], a[0:15]
	v_exp_f32_e32 v99, v65
	v_cvt_pk_bf16_f32 v89, v90, v91
	v_add_f32_e32 v64, v66, v96
	v_add_f32_e32 v65, v67, v97
	v_cvt_pk_bf16_f32 v90, v66, v67
	ds_read_b64_tr_b16 v[146:147], v108 offset:22528
	ds_read_b64_tr_b16 v[148:149], v108 offset:25088
	s_waitcnt lgkmcnt(4)
; DEV uint32_t pk2(float lo, float hi) { f32x2 v; v[0] = lo; v[1] = hi; bf16v2 b = __builtin_convertvector(v, bf16v2); return __builtin_bit_cast(uint32_t, b); }
; DEV f32x16 mfma32(bf16x8 a, bf16x8 b, f32x16 c) { return __builtin_amdgcn_mfma_f32_32x32x16_bf16(a, b, c, 0, 0, 0); }
; template <bool SAMPLE>
; DEV void attn_unit(CParams& p, int layer, int unit, float lam, float lam_init, char* lds, const int swave) {
;     ...
;       auto sm8 = [&](const f32x16& Sx, int r0, float nm, float& lsum) -> bf16x8 {
;         f32x2 c2; c2[0] = cexp; c2[1] = cexp;
;         f32x2 nm2; nm2[0] = nm; nm2[1] = nm;
;         union { u32x4 u; bf16x8 b; } x;
;         f32x2 sum2; sum2[0] = 0.f; sum2[1] = 0.f;
; #pragma unroll
;         for (int r = 0; r < 8; r += 2) {
;           f32x2 v; v[0] = Sx[r0 + r]; v[1] = Sx[r0 + r + 1];
;           v = v * c2 + nm2;
;           f32x2 ex; ex[0] = __builtin_amdgcn_exp2f(v[0]); ex[1] = __builtin_amdgcn_exp2f(v[1]);
;           sum2 += ex;
;           x.u[r >> 1] = pk2(ex[0], ex[1]);
;         }
;         lsum += sum2[0] + sum2[1];
;         return x.b;
;       };
;       qk(0);
;       pf[0][0] = sm8(S0, 0, nmc[0], ls[0]); pf[0][1] = sm8(S0, 8, nmc[0], ls[0]);
;       pf[0][2] = sm8(S1, 0, nmc[0], ls[0]); pf[0][3] = sm8(S1, 8, nmc[0], ls[0]);
;       qk(1);
;       if (!SAMPLE || t + 1 < ntiles) gloadV(tn);
; #pragma unroll
;       for (int sl = 0; sl < 4; ++sl) {
; #pragma unroll
;         for (int e = 0; e < 4; ++e) {
;           const bf16x8 vf = tr8(Vs, AV_B, sl * 16, e * 32, lane);
;           O1[e] = mfma32(vf, pf[0][sl], O1[e]);
;         }
;         pf[1][sl] = sm8(sl < 2 ? S0 : S1, (sl & 1) * 8, nmc[1], ls[1]);
	v_mfma_f32_32x32x16_bf16 a[32:47], v[100:103], v[92:95], a[32:47]
	ds_read_b64_tr_b16 v[150:151], v108 offset:22592
	ds_read_b64_tr_b16 v[154:155], v108 offset:22656
	ds_read_b64_tr_b16 v[158:159], v108 offset:22720
	ds_read_b64_tr_b16 v[152:153], v108 offset:25152
	ds_read_b64_tr_b16 v[156:157], v108 offset:25216
	ds_read_b64_tr_b16 v[160:161], v108 offset:25280
	v_fma_f32 v66, v210, s52, v48
	v_fma_f32 v67, v211, s52, v49
	v_cvt_pk_bf16_f32 v91, v98, v99
	v_exp_f32_e32 v66, v66
	v_exp_f32_e32 v67, v67
	s_waitcnt lgkmcnt(9)
	v_mfma_f32_32x32x16_bf16 a[64:79], v[122:125], v[92:95], a[64:79]
	v_add_f32_e32 v64, v98, v64
	v_add_f32_e32 v65, v99, v65
	v_fma_f32 v98, v216, s52, v48
	v_fma_f32 v99, v217, s52, v49
	s_waitcnt lgkmcnt(8)
	v_mfma_f32_32x32x16_bf16 a[96:111], v[142:145], v[92:95], a[96:111]
	v_fma_f32 v92, v212, s52, v48
	v_fma_f32 v93, v213, s52, v49
	v_exp_f32_e32 v98, v98
	v_exp_f32_e32 v94, v92
	v_exp_f32_e32 v95, v93
	v_cvt_pk_bf16_f32 v92, v66, v67
	v_exp_f32_e32 v99, v99
	ds_read_b64_tr_b16 v[162:163], v108 offset:27648
	ds_read_b64_tr_b16 v[164:165], v108 offset:30208
	s_waitcnt lgkmcnt(8)
	v_mfma_f32_32x32x16_bf16 a[0:15], v[146:149], v[88:91], a[0:15]
	v_add_f32_e64 v66, v94, v66
	v_add_f32_e64 v67, v95, v67
	v_fma_f32 v96, v214, s52, v48
	v_fma_f32 v97, v215, s52, v49
	ds_read_b64_tr_b16 v[166:167], v108 offset:27712
	ds_read_b64_tr_b16 v[170:171], v108 offset:27776
	ds_read_b64_tr_b16 v[174:175], v108 offset:27840
	ds_read_b64_tr_b16 v[168:169], v108 offset:30272
	ds_read_b64_tr_b16 v[172:173], v108 offset:30336
	ds_read_b64_tr_b16 v[176:177], v108 offset:30400
	v_exp_f32_e32 v96, v96
	v_exp_f32_e32 v97, v97
	s_waitcnt lgkmcnt(10)
	v_mfma_f32_32x32x16_bf16 a[32:47], v[150:153], v[88:91], a[32:47]
	v_fma_f32 v74, v218, s52, v48
	v_fma_f32 v75, v219, s52, v49
	v_fma_f32 v72, v220, s52, v48
	v_fma_f32 v73, v221, s52, v49
	v_exp_f32_e32 v74, v74
	v_exp_f32_e32 v75, v75
	v_cvt_pk_bf16_f32 v93, v94, v95
	s_waitcnt lgkmcnt(9)
	v_mfma_f32_32x32x16_bf16 a[64:79], v[154:157], v[88:91], a[64:79]
	v_cvt_pk_bf16_f32 v94, v96, v97
	v_cvt_pk_bf16_f32 v95, v98, v99
	v_fma_f32 v70, v222, s52, v48
	v_fma_f32 v71, v223, s52, v49
	s_waitcnt lgkmcnt(8)
	v_mfma_f32_32x32x16_bf16 a[96:111], v[158:161], v[88:91], a[96:111]
	v_exp_f32_e32 v88, v72
	v_exp_f32_e32 v89, v73
	v_exp_f32_e32 v70, v70
	v_exp_f32_e32 v71, v71
	v_fma_f32 v68, v224, s52, v48
	v_fma_f32 v69, v225, s52, v49
	v_cvt_pk_bf16_f32 v72, v74, v75
	s_waitcnt lgkmcnt(6)
	v_mfma_f32_32x32x16_bf16 a[0:15], v[162:165], v[92:95], a[0:15]
	v_add_f32_e64 v74, v88, v74
	v_add_f32_e64 v75, v89, v75
	v_exp_f32_e32 v90, v68
	v_exp_f32_e32 v91, v69
	ds_read_b64_tr_b16 v[178:179], v108 offset:32768
	ds_read_b64_tr_b16 v[180:181], v108 offset:35328
	ds_read_b64_tr_b16 v[182:183], v108 offset:32832
	ds_read_b64_tr_b16 v[186:187], v108 offset:32896
	ds_read_b64_tr_b16 v[190:191], v108 offset:32960
	ds_read_b64_tr_b16 v[184:185], v108 offset:35392
	ds_read_b64_tr_b16 v[188:189], v108 offset:35456
	ds_read_b64_tr_b16 v[192:193], v108 offset:35520
	v_add_f32_e32 v66, v96, v66
	v_add_f32_e32 v67, v97, v67
	v_add_f32_e32 v68, v70, v74
	v_add_f32_e32 v69, v71, v75
	s_waitcnt lgkmcnt(10)
	v_mfma_f32_32x32x16_bf16 a[32:47], v[166:169], v[92:95], a[32:47]
	v_add_f32_e64 v66, v98, v66
	v_add_f32_e64 v67, v99, v67
	v_accvgpr_read_b32 v98, a144
	v_cvt_pk_bf16_f32 v74, v70, v71
	v_accvgpr_read_b32 v71, a151
	v_accvgpr_read_b32 v70, a150
	v_accvgpr_read_b32 v97, a147
	v_accvgpr_read_b32 v96, a146
	s_waitcnt lgkmcnt(9)
	v_mfma_f32_32x32x16_bf16 a[64:79], v[170:173], v[92:95], a[64:79]
	v_accvgpr_read_b32 v99, a145
	v_cvt_pk_bf16_f32 v73, v88, v89
	v_cvt_pk_bf16_f32 v75, v90, v91
	v_fma_f32 v98, v98, s52, v52
	v_fma_f32 v99, v99, s52, v53
	v_fma_f32 v96, v96, s52, v52
	v_fma_f32 v97, v97, s52, v53
	v_fma_f32 v70, v70, s52, v52
	v_fma_f32 v71, v71, s52, v53
	v_exp_f32_e32 v104, v98
	s_waitcnt lgkmcnt(8)
	v_mfma_f32_32x32x16_bf16 a[96:111], v[174:177], v[92:95], a[96:111]
	v_accvgpr_read_b32 v95, a149
	v_accvgpr_read_b32 v94, a148
	v_fma_f32 v94, v94, s52, v52
	v_fma_f32 v95, v95, s52, v53
	v_exp_f32_e32 v105, v99
	v_exp_f32_e32 v106, v96
	v_exp_f32_e32 v107, v97
	v_exp_f32_e32 v108, v94
	s_waitcnt lgkmcnt(6)
	v_mfma_f32_32x32x16_bf16 a[0:15], v[178:181], v[72:75], a[0:15]
	v_exp_f32_e32 v109, v95
	v_add_f32_e32 v68, v90, v68
	v_add_f32_e32 v69, v91, v69
	v_accvgpr_read_b32 v89, a159
	v_accvgpr_read_b32 v88, a158
	v_accvgpr_read_b32 v91, a157
	v_accvgpr_read_b32 v90, a156
	v_accvgpr_read_b32 v93, a155
	s_waitcnt lgkmcnt(2)
	v_mfma_f32_32x32x16_bf16 a[32:47], v[182:185], v[72:75], a[32:47]
	v_accvgpr_read_b32 v92, a154
	v_accvgpr_read_b32 v95, a153
	v_accvgpr_read_b32 v94, a152
	v_fma_f32 v94, v94, s52, v52
	v_fma_f32 v95, v95, s52, v53
	v_fma_f32 v92, v92, s52, v52
	v_fma_f32 v93, v93, s52, v53
	v_fma_f32 v90, v90, s52, v52
	v_fma_f32 v91, v91, s52, v53
	v_exp_f32_e32 v120, v94
	s_waitcnt lgkmcnt(1)
	v_mfma_f32_32x32x16_bf16 a[64:79], v[186:189], v[72:75], a[64:79]
	v_exp_f32_e32 v121, v95
	v_accvgpr_read_b32 v133, a133
	v_accvgpr_read_b32 v132, a132
	v_accvgpr_read_b32 v139, a131
	v_accvgpr_read_b32 v138, a130
	v_fma_f32 v132, v132, s52, v52
	v_fma_f32 v133, v133, s52, v53
	v_accvgpr_read_b32 v115, a139
	s_waitcnt lgkmcnt(0)
; DEV f32x16 mfma32(bf16x8 a, bf16x8 b, f32x16 c) { return __builtin_amdgcn_mfma_f32_32x32x16_bf16(a, b, c, 0, 0, 0); }
; template <bool SAMPLE>
; DEV void attn_unit(CParams& p, int layer, int unit, float lam, float lam_init, char* lds, const int swave) {
;     ...
;       qk(0);
;       pf[0][0] = sm8(S0, 0, nmc[0], ls[0]); pf[0][1] = sm8(S0, 8, nmc[0], ls[0]);
;       pf[0][2] = sm8(S1, 0, nmc[0], ls[0]); pf[0][3] = sm8(S1, 8, nmc[0], ls[0]);
;       qk(1);
;       if (!SAMPLE || t + 1 < ntiles) gloadV(tn);
; #pragma unroll
;       for (int sl = 0; sl < 4; ++sl) {
; #pragma unroll
;         for (int e = 0; e < 4; ++e) {
;           const bf16x8 vf = tr8(Vs, AV_B, sl * 16, e * 32, lane);
;           O1[e] = mfma32(vf, pf[0][sl], O1[e]);
;         }
;         pf[1][sl] = sm8(sl < 2 ? S0 : S1, (sl & 1) * 8, nmc[1], ls[1]);
;       }
; #pragma unroll
;       for (int sl = 0; sl < 4; ++sl)
; #pragma unroll
;         for (int e = 0; e < 4; ++e) {
;           const bf16x8 vf = tr8(Vs, AV_B, sl * 16, e * 32, lane);
;           O2[e] = mfma32(vf, pf[1][sl], O2[e]);
;         }
;     }
;     if (t >= my_tiles && (!SAMPLE || t + 1 < ntiles)) gloadV(tn);
;     if (!SAMPLE || t + 1 < ntiles) lwrite((t + 1) & 1);
	v_mfma_f32_32x32x16_bf16 a[96:111], v[190:193], v[72:75], a[96:111]
	v_exp_f32_e32 v74, v70
	v_exp_f32_e32 v75, v71
	v_cvt_pk_bf16_f32 v70, v104, v105
	v_cvt_pk_bf16_f32 v71, v106, v107
	v_cvt_pk_bf16_f32 v72, v108, v109
	v_cvt_pk_bf16_f32 v73, v74, v75
	v_exp_f32_e32 v132, v132
	s_nop 0
	v_mfma_f32_32x32x16_bf16 a[16:31], v[116:119], v[70:73], a[16:31]
	v_add_f32_e64 v104, v106, v104
	v_add_f32_e64 v105, v107, v105
	v_accvgpr_read_b32 v106, a128
	v_accvgpr_read_b32 v119, a135
	v_accvgpr_read_b32 v118, a134
	v_accvgpr_read_b32 v107, a129
	v_add_f32_e32 v104, v108, v104
	v_add_f32_e32 v105, v109, v105
	v_fma_f32 v106, v106, s52, v52
	v_fma_f32 v107, v107, s52, v53
	v_mfma_f32_32x32x16_bf16 a[48:63], v[100:103], v[70:73], a[48:63]
	v_cvt_pk_bf16_f32 v100, v120, v121
	v_fma_f32 v108, v138, s52, v52
	v_fma_f32 v109, v139, s52, v53
	v_exp_f32_e32 v106, v106
	v_exp_f32_e32 v107, v107
	v_exp_f32_e32 v108, v108
	v_exp_f32_e32 v109, v109
	v_exp_f32_e32 v133, v133
	v_mfma_f32_32x32x16_bf16 a[80:95], v[122:125], v[70:73], a[80:95]
	v_exp_f32_e32 v122, v92
	v_exp_f32_e32 v123, v93
	v_exp_f32_e32 v124, v90
	v_exp_f32_e32 v125, v91
	v_add_f32_e32 v74, v74, v104
	v_add_f32_e32 v75, v75, v105
	v_cvt_pk_bf16_f32 v101, v122, v123
	v_mfma_f32_32x32x16_bf16 a[112:127], v[142:145], v[70:73], a[112:127]
	v_fma_f32 v70, v88, s52, v52
	v_fma_f32 v71, v89, s52, v53
	v_cvt_pk_bf16_f32 v102, v124, v125
	v_exp_f32_e32 v126, v70
	v_exp_f32_e32 v127, v71
	v_add_f32_e32 v104, v122, v120
	v_add_f32_e32 v105, v123, v121
	v_cvt_pk_bf16_f32 v103, v126, v127
	v_accvgpr_read_b32 v117, a137
	v_accvgpr_read_b32 v116, a136
	v_mfma_f32_32x32x16_bf16 a[16:31], v[146:149], v[100:103], a[16:31]
	v_add_f32_e64 v104, v124, v104
	v_add_f32_e64 v105, v125, v105
	v_accvgpr_read_b32 v114, a138
	v_add_f32_e64 v120, v126, v104
	v_add_f32_e64 v121, v127, v105
	v_accvgpr_read_b32 v111, a143
	v_accvgpr_read_b32 v110, a142
	v_accvgpr_read_b32 v113, a141
	v_mfma_f32_32x32x16_bf16 a[48:63], v[150:153], v[100:103], a[48:63]
	v_accvgpr_read_b32 v112, a140
	v_add_f32_e64 v104, v108, v106
	v_add_f32_e64 v105, v109, v107
	v_fma_f32 v112, v112, s52, v52
	v_fma_f32 v113, v113, s52, v53
	v_add_f32_e32 v104, v132, v104
	v_add_f32_e32 v105, v133, v105
	v_exp_f32_e32 v112, v112
	v_exp_f32_e32 v113, v113
	v_mfma_f32_32x32x16_bf16 a[80:95], v[154:157], v[100:103], a[80:95]
	s_andn2_b32 s8, 1, s37
	s_mul_i32 s8, s8, 0x9400
	s_add_i32 s8, s8, 16
	s_waitcnt vmcnt(0)
	v_add3_u32 v54, s8, v77, v76
	ds_write_b128 v54, v[4:7]
	v_add3_u32 v55, s8, v78, v76
	ds_write_b128 v55, v[194:197] offset:17408
	v_mfma_f32_32x32x16_bf16 a[112:127], v[158:161], v[100:103], a[112:127]
	v_add3_u32 v56, s8, v79, v76
	ds_write_b128 v56, v[0:3]
	v_add3_u32 v57, s8, v80, v76
	ds_write_b128 v57, v[198:201] offset:17408
	v_fma_f32 v100, v118, s52, v52
	v_fma_f32 v101, v119, s52, v53
	v_cvt_pk_bf16_f32 v102, v132, v133
	v_exp_f32_e32 v118, v100
	v_exp_f32_e32 v119, v101
	v_cvt_pk_bf16_f32 v100, v106, v107
	v_cvt_pk_bf16_f32 v101, v108, v109
	v_fma_f32 v106, v116, s52, v52
	v_fma_f32 v107, v117, s52, v53
	v_cvt_pk_bf16_f32 v103, v118, v119
	v_exp_f32_e32 v106, v106
	v_exp_f32_e32 v107, v107
	v_mfma_f32_32x32x16_bf16 a[16:31], v[162:165], v[100:103], a[16:31]
	v_fma_f32 v108, v114, s52, v52
	v_fma_f32 v109, v115, s52, v53
	v_add_f32_e64 v114, v118, v104
	v_add_f32_e64 v115, v119, v105
	v_exp_f32_e32 v108, v108
	v_exp_f32_e32 v109, v109
	v_add_f32_e64 v116, v106, 0
	v_add_f32_e64 v117, v107, 0
	v_cvt_pk_bf16_f32 v104, v106, v107
	v_add_f32_e32 v106, v108, v116
	v_add_f32_e32 v107, v109, v117
	v_mfma_f32_32x32x16_bf16 a[48:63], v[166:169], v[100:103], a[48:63]
	v_cvt_pk_bf16_f32 v105, v108, v109
	v_mfma_f32_32x32x16_bf16 a[80:95], v[170:173], v[100:103], a[80:95]
	v_add3_u32 v58, s8, v81, v76
	ds_write_b128 v58, v[12:15]
	v_add3_u32 v59, s8, v82, v76
	ds_write_b128 v59, v[202:205] offset:17408
	v_mfma_f32_32x32x16_bf16 a[112:127], v[174:177], v[100:103], a[112:127]
	v_add3_u32 v60, s8, v83, v76
	ds_write_b128 v60, v[8:11]
	v_add3_u32 v61, s8, v84, v76
	ds_write_b128 v61, v[206:209] offset:17408
	v_fma_f32 v100, v110, s52, v52
	v_fma_f32 v101, v111, s52, v53
	v_add_f32_e64 v102, v112, v106
	v_add_f32_e64 v103, v113, v107
	v_exp_f32_e32 v100, v100
	v_exp_f32_e32 v101, v101
	v_cvt_pk_bf16_f32 v106, v112, v113
	v_cvt_pk_bf16_f32 v107, v100, v101
	s_nop 1
	v_mfma_f32_32x32x16_bf16 a[16:31], v[178:181], v[104:107], a[16:31]
	v_add_f32_e64 v100, v100, v102
	v_add_f32_e64 v101, v101, v103
	v_add_f32_e32 v62, v62, v63
	v_add_f32_e32 v74, v74, v75
	v_add_f32_e32 v64, v64, v65
	v_add_f32_e32 v120, v120, v121
	v_add_f32_e32 v66, v66, v67
	v_mfma_f32_32x32x16_bf16 a[48:63], v[182:185], v[104:107], a[48:63]
	v_add_f32_e32 v114, v114, v115
	v_add_f32_e32 v68, v68, v69
	v_add_f32_e32 v100, v100, v101
	v_add_f32_e32 v62, v130, v62
	v_add_f32_e32 v74, v131, v74
	v_mfma_f32_32x32x16_bf16 a[80:95], v[186:189], v[104:107], a[80:95]
	v_add_f32_e32 v62, v64, v62
	v_add_f32_e32 v74, v120, v74
	v_add_f32_e32 v62, v66, v62
	v_add_f32_e32 v74, v114, v74
	v_mfma_f32_32x32x16_bf16 a[112:127], v[190:193], v[104:107], a[112:127]
	v_add_f32_e32 v130, v68, v62
	v_add_f32_e32 v131, v100, v74
	s_branch .Lattn_tail

; template <bool SAMPLE>
; DEV void attn_unit(CParams& p, int layer, int unit, float lam, float lam_init, char* lds, const int swave) {
;     ...
;   auto kbase = [&](int t, int i, unsigned& voff, size_t& vdelta) -> const char* {
;     if (sample && t < 32) { voff = voffC; vdelta = W_VC - W_KC; return ws + W_KC + ((size_t)(b * 2048 + t * 64 + 16 * i) * 512 + head * 128) * 2; }
;     voff = voffP; vdelta = (size_t)(C_V - C_K) * 2;
;     if (sample) return (const char*)proj + ((size_t)(TP + b * 16) * PW + C_K + head * 128) * 2;
;     return (const char*)proj + ((size_t)(b * 16384 + t * 64 + 16 * i) * PW + C_K + head * 128) * 2;
;   };
;   auto gloadK = [&](int t) {
; #pragma unroll
;     for (int i = 0; i < 4; ++i) { unsigned voff; size_t vd; const char* kb = kbase(t, i, voff, vd); rk[i] = *(const u32x4*)(kb + voff); }
;   };
;     ...
;   for (int t = 0; t < ntiles; ++t) {
;     const int tn = SAMPLE ? t + 1 : (t + 1 < ntiles ? t + 1 : t);
;     if (!SAMPLE || t + 1 < ntiles) gloadK(tn);
;     if (t < my_tiles) {
;       const char* Ks = lds + (t & 1) * A_BUF; const char* Vs = Ks + A_KT;
;       bf16x8 pf[2][4];
;       f32x16 S0, S1;
;       auto qk = [&](int br) {
;         const f32x16 zc = {0.f, 0.f, 0.f, 0.f, 0.f, 0.f, 0.f, 0.f, 0.f, 0.f, 0.f, 0.f, 0.f, 0.f, 0.f, 0.f};
; #pragma unroll
;         for (int ks = 0; ks < 4; ++ks) {
;           const bf16x8 k0 = lds_read8(Ks + lr * AK_B + (br * 64 + ks * 16 + hh * 8) * 2);
;           const bf16x8 k1 = lds_read8(Ks + (32 + lr) * AK_B + (br * 64 + ks * 16 + hh * 8) * 2);
;           S0 = mfma32(k0, qf[br][ks], ks == 0 ? zc : S0); S1 = mfma32(k1, qf[br][ks], ks == 0 ? zc : S1);
;         }
;         if (sample && t == 32) {
; #pragma unroll
;           for (int r = 0; r < 16; ++r) { if (r >= 8) S0[r] = -1e30f; S1[r] = -1e30f; }
;         }
;       };
;       auto sm8 = [&](const f32x16& Sx, int r0, float nm, float& lsum) -> bf16x8 {
;         f32x2 c2; c2[0] = cexp; c2[1] = cexp;
;         f32x2 nm2; nm2[0] = nm; nm2[1] = nm;
;         union { u32x4 u; bf16x8 b; } x;
;         f32x2 sum2; sum2[0] = 0.f; sum2[1] = 0.f;
; #pragma unroll
;         for (int r = 0; r < 8; r += 2) {
;           f32x2 v; v[0] = Sx[r0 + r]; v[1] = Sx[r0 + r + 1];
;           v = v * c2 + nm2;
;           f32x2 ex; ex[0] = __builtin_amdgcn_exp2f(v[0]); ex[1] = __builtin_amdgcn_exp2f(v[1]);
;           sum2 += ex;
.LBB0_256:
	s_cmp_lt_u32 s31, 31
	s_cselect_b64 s[2:3], -1, 0
	s_add_i32 s8, s15, 0xffff4000
	s_add_u32 s36, s23, s8
	s_addc_u32 s37, s28, 0
	s_and_b64 s[8:9], s[2:3], exec
	s_cselect_b32 s9, s37, s30
	s_cselect_b32 s8, s36, s29
	s_add_i32 s36, s15, 0xffff8000
	s_add_u32 s38, s23, s36
	s_addc_u32 s39, s28, 0
	s_and_b64 s[36:37], s[2:3], exec
	s_cselect_b32 s57, s39, s30
	s_cselect_b32 s56, s38, s29
	s_add_i32 s36, s15, 0xffffc000
	s_add_u32 s38, s23, s36
	s_addc_u32 s39, s28, 0
	s_and_b64 s[36:37], s[2:3], exec
	s_cselect_b32 s61, s39, s30
	s_cselect_b32 s60, s38, s29
	s_add_u32 s38, s23, s15
	s_addc_u32 s39, s28, 0
	v_cndmask_b32_e64 v240, v52, v32, s[2:3]
	s_and_b64 s[36:37], s[2:3], exec
	global_load_dwordx4 v[4:7], v240, s[8:9]
	global_load_dwordx4 v[0:3], v240, s[56:57]
	s_cselect_b32 s81, s39, s30
	s_cselect_b32 s80, s38, s29
	global_load_dwordx4 v[12:15], v240, s[60:61]
	global_load_dwordx4 v[8:11], v240, s[80:81]
	s_cmp_ge_u32 s31, s22
	s_cselect_b64 s[82:83], -1, 0
	s_and_b64 vcc, exec, s[82:83]
	s_cbranch_vccnz .LBB0_258
	s_bitcmp1_b32 s31, 0
	s_cselect_b32 s36, 0x9400, 0
	s_add_i32 s36, s36, 16
	v_add_u32_e32 v116, s36, v44
	v_add_u32_e32 v20, v116, v51
	ds_read_b128 v[16:19], v20
	ds_read_b128 v[20:23], v20 offset:8704
	v_add_u32_e32 v24, v116, v42
	v_add_u32_e32 v28, v116, v45
	v_add_u32_e32 v114, v116, v47
	s_waitcnt lgkmcnt(1)
	v_mfma_f32_32x32x16_bf16 a[128:143], v[16:19], v[88:91], 0
	v_add_u32_e32 v117, v116, v46
	s_waitcnt lgkmcnt(0)
	v_mfma_f32_32x32x16_bf16 a[160:175], v[20:23], v[88:91], 0
	v_add_u32_e32 v20, v116, v41
	ds_read_b128 v[16:19], v20
	ds_read_b128 v[20:23], v20 offset:8704
	s_waitcnt lgkmcnt(1)
	v_mfma_f32_32x32x16_bf16 a[128:143], v[16:19], v[84:87], a[128:143]
	s_waitcnt lgkmcnt(0)
	v_mfma_f32_32x32x16_bf16 a[160:175], v[20:23], v[84:87], a[160:175]
	v_add_u32_e32 v20, v116, v43
	ds_read_b128 v[16:19], v20
	ds_read_b128 v[20:23], v20 offset:8704
	s_waitcnt lgkmcnt(1)
	v_mfma_f32_32x32x16_bf16 a[128:143], v[16:19], v[80:83], a[128:143]
	ds_read_b128 v[16:19], v24
	ds_read_b128 v[24:27], v24 offset:8704
	s_waitcnt lgkmcnt(1)
	v_mfma_f32_32x32x16_bf16 a[128:143], v[16:19], v[76:79], a[128:143]
	v_mfma_f32_32x32x16_bf16 a[160:175], v[20:23], v[80:83], a[160:175]
	ds_read_b128 v[20:23], v28 offset:8704
	ds_read_b128 v[92:95], v28
	s_nop 8
	v_accvgpr_read_b32 v97, a131
	v_accvgpr_read_b32 v96, a130
	v_fma_f32 v96, v96, s52, v34
	v_fma_f32 v97, v97, s52, v35
	v_accvgpr_read_b32 v19, a143
	s_waitcnt lgkmcnt(0)
	v_mfma_f32_32x32x16_bf16 a[144:159], v[92:95], v[72:75], 0
	v_accvgpr_read_b32 v92, a128
	v_accvgpr_read_b32 v93, a129
	v_fma_f32 v92, v92, s52, v34
	v_fma_f32 v93, v93, s52, v35
	v_exp_f32_e32 v112, v96
	v_exp_f32_e32 v110, v92
	v_exp_f32_e32 v111, v93
	ds_read_b128 v[92:95], v114
	v_exp_f32_e32 v113, v97
	v_accvgpr_read_b32 v18, a142
	v_accvgpr_read_b32 v37, a141
	v_accvgpr_read_b32 v36, a140
	v_accvgpr_read_b32 v17, a139
	v_accvgpr_read_b32 v16, a138
	v_accvgpr_read_b32 v101, a137
	v_accvgpr_read_b32 v100, a136
	v_accvgpr_read_b32 v99, a135
	v_accvgpr_read_b32 v98, a134
	v_accvgpr_read_b32 v103, a133
	v_accvgpr_read_b32 v102, a132
	v_mfma_f32_32x32x16_bf16 a[128:143], v[20:23], v[72:75], 0
	v_add_f32_e64 v20, v110, 0
	v_add_f32_e64 v21, v111, 0
	v_cvt_pk_bf16_f32 v96, v110, v111
	v_add_f32_e64 v110, v112, v20
	v_add_f32_e64 v111, v113, v21
	ds_read_b128 v[20:23], v114 offset:8704
	v_fma_f32 v98, v98, s52, v34
	v_fma_f32 v99, v99, s52, v35
	v_fma_f32 v16, v16, s52, v34
	v_fma_f32 v17, v17, s52, v35
	v_exp_f32_e32 v114, v98
	s_waitcnt lgkmcnt(1)
	v_mfma_f32_32x32x16_bf16 a[144:159], v[92:95], v[68:71], a[144:159]
	v_fma_f32 v92, v102, s52, v34
	v_fma_f32 v93, v103, s52, v35
	v_cvt_pk_bf16_f32 v97, v112, v113
	v_exp_f32_e32 v102, v92
	v_exp_f32_e32 v103, v93
	ds_read_b128 v[92:95], v117
	v_add_u32_e32 v112, v116, v48
	v_exp_f32_e32 v115, v99
	s_waitcnt lgkmcnt(1)
	v_mfma_f32_32x32x16_bf16 a[128:143], v[20:23], v[68:71], a[128:143]
	v_add_f32_e64 v20, v102, v110
	v_add_f32_e64 v21, v103, v111
	v_cvt_pk_bf16_f32 v98, v102, v103
	v_fma_f32 v22, v100, s52, v34
	v_fma_f32 v23, v101, s52, v35
	ds_read_b128 v[100:103], v117 offset:8704
	v_exp_f32_e32 v22, v22
	v_exp_f32_e32 v23, v23
	v_exp_f32_e32 v110, v16
	v_exp_f32_e32 v111, v17
	s_waitcnt lgkmcnt(1)
	v_mfma_f32_32x32x16_bf16 a[144:159], v[92:95], v[64:67], a[144:159]
	ds_read_b128 v[92:95], v112
	v_cvt_pk_bf16_f32 v16, v22, v23
	v_cvt_pk_bf16_f32 v17, v110, v111
	v_fma_f32 v36, v36, s52, v34
	v_fma_f32 v37, v37, s52, v35
	v_cvt_pk_bf16_f32 v99, v114, v115
	v_exp_f32_e32 v36, v36
	v_exp_f32_e32 v37, v37
	s_waitcnt lgkmcnt(1)
	v_mfma_f32_32x32x16_bf16 a[128:143], v[100:103], v[64:67], a[128:143]
	v_add_f32_e64 v100, v22, 0
	v_add_f32_e64 v101, v23, 0
	v_fma_f32 v18, v18, s52, v34
	v_fma_f32 v19, v19, s52, v35
	v_add_f32_e64 v22, v110, v100
	v_add_f32_e64 v23, v111, v101
	v_add3_u32 v110, s36, v50, v49
	ds_read_b128 v[100:103], v112 offset:8704
	ds_read_b64_tr_b16 v[142:143], v110 offset:17408
	ds_read_b64_tr_b16 v[144:145], v110 offset:19968
	ds_read_b64_tr_b16 v[146:147], v110 offset:17472
	ds_read_b64_tr_b16 v[150:151], v110 offset:17536
	ds_read_b64_tr_b16 v[154:155], v110 offset:17600
	ds_read_b64_tr_b16 v[148:149], v110 offset:20032
	ds_read_b64_tr_b16 v[152:153], v110 offset:20096
	ds_read_b64_tr_b16 v[156:157], v110 offset:20160
	v_mfma_f32_32x32x16_bf16 a[160:175], v[24:27], v[76:79], a[160:175]
	v_add_f32_e64 v22, v36, v22
	v_add_f32_e64 v23, v37, v23
	ds_read_b64_tr_b16 v[158:159], v110 offset:22528
	ds_read_b64_tr_b16 v[160:161], v110 offset:25088
	ds_read_b64_tr_b16 v[162:163], v110 offset:22592
	ds_read_b64_tr_b16 v[166:167], v110 offset:22656
	ds_read_b64_tr_b16 v[170:171], v110 offset:22720
	ds_read_b64_tr_b16 v[164:165], v110 offset:25152
	ds_read_b64_tr_b16 v[168:169], v110 offset:25216
	ds_read_b64_tr_b16 v[172:173], v110 offset:25280
	ds_read_b64_tr_b16 v[174:175], v110 offset:27648
	ds_read_b64_tr_b16 v[176:177], v110 offset:30208
	ds_read_b64_tr_b16 v[178:179], v110 offset:27712
	ds_read_b64_tr_b16 v[182:183], v110 offset:27776
	ds_read_b64_tr_b16 v[186:187], v110 offset:27840
	ds_read_b64_tr_b16 v[180:181], v110 offset:30272
	ds_read_b64_tr_b16 v[184:185], v110 offset:30336
	ds_read_b64_tr_b16 v[188:189], v110 offset:30400
	s_and_b64 s[36:37], s[2:3], exec
	s_cselect_b32 s38, s43, 0x400
	s_waitcnt lgkmcnt(14)
; DEV uint32_t pk2(float lo, float hi) { f32x2 v; v[0] = lo; v[1] = hi; bf16v2 b = __builtin_convertvector(v, bf16v2); return __builtin_bit_cast(uint32_t, b); }
; DEV f32x16 mfma32(bf16x8 a, bf16x8 b, f32x16 c) { return __builtin_amdgcn_mfma_f32_32x32x16_bf16(a, b, c, 0, 0, 0); }
; template <bool SAMPLE>
; DEV void attn_unit(CParams& p, int layer, int unit, float lam, float lam_init, char* lds, const int swave) {
;     ...
;       auto sm8 = [&](const f32x16& Sx, int r0, float nm, float& lsum) -> bf16x8 {
;         f32x2 c2; c2[0] = cexp; c2[1] = cexp;
;         f32x2 nm2; nm2[0] = nm; nm2[1] = nm;
;         union { u32x4 u; bf16x8 b; } x;
;         f32x2 sum2; sum2[0] = 0.f; sum2[1] = 0.f;
; #pragma unroll
;         for (int r = 0; r < 8; r += 2) {
;           f32x2 v; v[0] = Sx[r0 + r]; v[1] = Sx[r0 + r + 1];
;           v = v * c2 + nm2;
;           f32x2 ex; ex[0] = __builtin_amdgcn_exp2f(v[0]); ex[1] = __builtin_amdgcn_exp2f(v[1]);
;           sum2 += ex;
;           x.u[r >> 1] = pk2(ex[0], ex[1]);
;         }
;         lsum += sum2[0] + sum2[1];
;         return x.b;
;       };
;       qk(0);
;       pf[0][0] = sm8(S0, 0, nmc[0], ls[0]); pf[0][1] = sm8(S0, 8, nmc[0], ls[0]);
;       pf[0][2] = sm8(S1, 0, nmc[0], ls[0]); pf[0][3] = sm8(S1, 8, nmc[0], ls[0]);
;       qk(1);
;       if (!SAMPLE || t + 1 < ntiles) gloadV(tn);
; #pragma unroll
;       for (int sl = 0; sl < 4; ++sl) {
; #pragma unroll
;         for (int e = 0; e < 4; ++e) {
;           const bf16x8 vf = tr8(Vs, AV_B, sl * 16, e * 32, lane);
;           O1[e] = mfma32(vf, pf[0][sl], O1[e]);
;         }
;         pf[1][sl] = sm8(sl < 2 ? S0 : S1, (sl & 1) * 8, nmc[1], ls[1]);
;       }
; #pragma unroll
;       for (int sl = 0; sl < 4; ++sl)
; #pragma unroll
;         for (int e = 0; e < 4; ++e) {
;           const bf16x8 vf = tr8(Vs, AV_B, sl * 16, e * 32, lane);
;           O2[e] = mfma32(vf, pf[1][sl], O2[e]);
;         }
	v_mfma_f32_32x32x16_bf16 a[0:15], v[142:145], v[96:99], a[0:15]
	v_accvgpr_read_b32 v109, a163
	v_accvgpr_read_b32 v108, a162
	v_accvgpr_read_b32 v39, a169
	v_accvgpr_read_b32 v38, a168
	v_accvgpr_read_b32 v105, a167
	v_accvgpr_read_b32 v104, a166
	v_accvgpr_read_b32 v107, a165
	v_mfma_f32_32x32x16_bf16 a[32:47], v[146:149], v[96:99], a[32:47]
	v_accvgpr_read_b32 v106, a164
	v_accvgpr_read_b32 v29, a171
	v_accvgpr_read_b32 v28, a170
	v_fma_f32 v38, v38, s52, v34
	v_fma_f32 v39, v39, s52, v35
	v_accvgpr_read_b32 v27, a173
	v_accvgpr_read_b32 v26, a172
	v_exp_f32_e32 v38, v38
	v_mfma_f32_32x32x16_bf16 a[64:79], v[150:153], v[96:99], a[64:79]
	v_exp_f32_e32 v39, v39
	v_fma_f32 v28, v28, s52, v34
	v_fma_f32 v29, v29, s52, v35
	v_accvgpr_read_b32 v25, a175
	v_accvgpr_read_b32 v24, a174
	v_exp_f32_e32 v28, v28
	v_exp_f32_e32 v29, v29
	v_fma_f32 v26, v26, s52, v34
	v_fma_f32 v27, v27, s52, v35
	v_mfma_f32_32x32x16_bf16 a[96:111], v[154:157], v[96:99], a[96:111]
	v_exp_f32_e32 v26, v26
	v_exp_f32_e32 v27, v27
	v_fma_f32 v24, v24, s52, v34
	v_fma_f32 v25, v25, s52, v35
	v_add_f32_e64 v98, v38, 0
	v_add_f32_e64 v99, v39, 0
	v_exp_f32_e32 v24, v24
	v_exp_f32_e32 v25, v25
	v_cvt_pk_bf16_f32 v96, v38, v39
	v_mfma_f32_32x32x16_bf16 a[144:159], v[92:95], v[60:63], a[144:159]
	v_exp_f32_e32 v92, v18
	v_cvt_pk_bf16_f32 v18, v36, v37
	v_accvgpr_read_b32 v36, a160
	v_exp_f32_e32 v93, v19
	v_accvgpr_read_b32 v37, a161
	v_fma_f32 v36, v36, s52, v34
	v_fma_f32 v37, v37, s52, v35
	v_fma_f32 v94, v108, s52, v34
	v_fma_f32 v95, v109, s52, v35
	v_exp_f32_e32 v36, v36
	v_exp_f32_e32 v37, v37
	v_exp_f32_e32 v94, v94
	v_exp_f32_e32 v95, v95
	v_cvt_pk_bf16_f32 v19, v92, v93
	v_mfma_f32_32x32x16_bf16 a[128:143], v[100:103], v[60:63], a[128:143]
	v_add_f32_e64 v100, v36, 0
	v_add_f32_e64 v101, v37, 0
	v_add_f32_e64 v22, v92, v22
	v_add_f32_e64 v23, v93, v23
	v_cvt_pk_bf16_f32 v92, v36, v37
	v_add_f32_e32 v36, v94, v100
	v_add_f32_e32 v37, v95, v101
	v_fma_f32 v100, v106, s52, v34
	v_fma_f32 v101, v107, s52, v35
	v_fma_f32 v102, v104, s52, v34
	v_fma_f32 v103, v105, s52, v35
	v_exp_f32_e32 v100, v100
	v_mfma_f32_32x32x16_bf16 a[0:15], v[158:161], v[16:19], a[0:15]
	v_exp_f32_e32 v101, v101
	v_exp_f32_e32 v102, v102
	v_exp_f32_e32 v103, v103
	v_cvt_pk_bf16_f32 v93, v94, v95
	v_cvt_pk_bf16_f32 v94, v100, v101
	v_add_f32_e32 v38, v28, v98
	v_add_f32_e32 v39, v29, v99
	v_cvt_pk_bf16_f32 v95, v102, v103
	s_waitcnt lgkmcnt(10)
	v_mfma_f32_32x32x16_bf16 a[32:47], v[162:165], v[16:19], a[32:47]
	v_add_f32_e64 v36, v100, v36
	v_add_f32_e64 v37, v101, v37
	v_cvt_pk_bf16_f32 v98, v26, v27
	v_add_f32_e64 v36, v102, v36
	v_add_f32_e64 v37, v103, v37
	v_cvt_pk_bf16_f32 v99, v24, v25
	v_accvgpr_read_b32 v103, a147
	v_accvgpr_read_b32 v102, a146
	ds_read_b64_tr_b16 v[190:191], v110 offset:32768
	ds_read_b64_tr_b16 v[192:193], v110 offset:35328
	s_waitcnt lgkmcnt(11)
	v_mfma_f32_32x32x16_bf16 a[64:79], v[166:169], v[16:19], a[64:79]
	ds_read_b64_tr_b16 v[194:195], v110 offset:32832
	ds_read_b64_tr_b16 v[198:199], v110 offset:32896
	ds_read_b64_tr_b16 v[202:203], v110 offset:32960
	ds_read_b64_tr_b16 v[196:197], v110 offset:35392
	ds_read_b64_tr_b16 v[200:201], v110 offset:35456
	ds_read_b64_tr_b16 v[204:205], v110 offset:35520
	s_add_u32 s36, s80, s38
	s_addc_u32 s37, s81, 0
	v_cvt_pk_bf16_f32 v97, v28, v29
	v_accvgpr_read_b32 v101, a153
	v_accvgpr_read_b32 v100, a152
	v_accvgpr_read_b32 v29, a157
	s_waitcnt lgkmcnt(14)
	v_mfma_f32_32x32x16_bf16 a[96:111], v[170:173], v[16:19], a[96:111]
	v_add_f32_e64 v16, v26, v38
	v_add_f32_e64 v17, v27, v39
	v_accvgpr_read_b32 v27, a149
	v_add_f32_e64 v16, v24, v16
	v_add_f32_e64 v17, v25, v17
	v_accvgpr_read_b32 v25, a151
	v_accvgpr_read_b32 v24, a150
	v_accvgpr_read_b32 v26, a148
	v_fma_f32 v26, v26, s52, v30
	v_fma_f32 v27, v27, s52, v31
	v_mfma_f32_32x32x16_bf16 a[0:15], v[174:177], v[92:95], a[0:15]
	v_fma_f32 v24, v24, s52, v30
	v_fma_f32 v25, v25, s52, v31
	v_exp_f32_e32 v124, v26
	v_exp_f32_e32 v125, v27
	v_exp_f32_e32 v126, v24
	v_exp_f32_e32 v127, v25
	v_accvgpr_read_b32 v19, a159
	v_cvt_pk_bf16_f32 v26, v124, v125
	s_waitcnt lgkmcnt(10)
	v_mfma_f32_32x32x16_bf16 a[32:47], v[178:181], v[92:95], a[32:47]
	v_cvt_pk_bf16_f32 v27, v126, v127
	v_accvgpr_read_b32 v18, a158
	v_accvgpr_read_b32 v28, a156
	v_accvgpr_read_b32 v39, a155
	v_accvgpr_read_b32 v38, a154
	v_fma_f32 v38, v38, s52, v30
	v_fma_f32 v39, v39, s52, v31
	v_fma_f32 v28, v28, s52, v30
	v_fma_f32 v29, v29, s52, v31
	s_waitcnt lgkmcnt(9)
	v_mfma_f32_32x32x16_bf16 a[64:79], v[182:185], v[92:95], a[64:79]
	v_fma_f32 v18, v18, s52, v30
	v_fma_f32 v19, v19, s52, v31
	v_exp_f32_e32 v38, v38
	v_exp_f32_e32 v39, v39
	v_exp_f32_e32 v28, v28
	v_exp_f32_e32 v29, v29
	v_exp_f32_e32 v18, v18
	v_exp_f32_e32 v19, v19
	s_waitcnt lgkmcnt(8)
	v_mfma_f32_32x32x16_bf16 a[96:111], v[186:189], v[92:95], a[96:111]
	v_accvgpr_read_b32 v92, a144
	v_accvgpr_read_b32 v93, a145
	v_fma_f32 v92, v92, s52, v30
	v_fma_f32 v93, v93, s52, v31
	v_accvgpr_read_b32 v117, a135
	v_exp_f32_e32 v120, v92
	v_exp_f32_e32 v121, v93
	v_fma_f32 v92, v102, s52, v30
	v_fma_f32 v93, v103, s52, v31
	s_waitcnt lgkmcnt(6)
	v_mfma_f32_32x32x16_bf16 a[0:15], v[190:193], v[96:99], a[0:15]
	v_exp_f32_e32 v122, v92
	v_exp_f32_e32 v123, v93
	v_lshl_add_u64 v[92:93], s[36:37], 0, v[240:241]
	s_add_u32 s36, s60, s38
	s_addc_u32 s37, s61, 0
	global_load_dwordx4 v[104:107], v[92:93], off
	v_lshl_add_u64 v[92:93], s[36:37], 0, v[240:241]
	s_add_u32 s36, s56, s38
	s_waitcnt lgkmcnt(2)
; DEV f32x16 mfma32(bf16x8 a, bf16x8 b, f32x16 c) { return __builtin_amdgcn_mfma_f32_32x32x16_bf16(a, b, c, 0, 0, 0); }
; template <bool SAMPLE>
; DEV void attn_unit(CParams& p, int layer, int unit, float lam, float lam_init, char* lds, const int swave) {
;     ...
;       qk(0);
;       pf[0][0] = sm8(S0, 0, nmc[0], ls[0]); pf[0][1] = sm8(S0, 8, nmc[0], ls[0]);
;       pf[0][2] = sm8(S1, 0, nmc[0], ls[0]); pf[0][3] = sm8(S1, 8, nmc[0], ls[0]);
;       qk(1);
;       if (!SAMPLE || t + 1 < ntiles) gloadV(tn);
; #pragma unroll
;       for (int sl = 0; sl < 4; ++sl) {
; #pragma unroll
;         for (int e = 0; e < 4; ++e) {
;           const bf16x8 vf = tr8(Vs, AV_B, sl * 16, e * 32, lane);
;           O1[e] = mfma32(vf, pf[0][sl], O1[e]);
;         }
;         pf[1][sl] = sm8(sl < 2 ? S0 : S1, (sl & 1) * 8, nmc[1], ls[1]);
;       }
; #pragma unroll
;       for (int sl = 0; sl < 4; ++sl)
; #pragma unroll
;         for (int e = 0; e < 4; ++e) {
;           const bf16x8 vf = tr8(Vs, AV_B, sl * 16, e * 32, lane);
;           O2[e] = mfma32(vf, pf[1][sl], O2[e]);
;         }
	v_mfma_f32_32x32x16_bf16 a[32:47], v[194:197], v[96:99], a[32:47]
	v_cvt_pk_bf16_f32 v24, v120, v121
	v_cvt_pk_bf16_f32 v25, v122, v123
	s_addc_u32 s37, s57, 0
	global_load_dwordx4 v[92:95], v[92:93], off
	v_add_f32_e64 v120, v120, 0
	v_add_f32_e64 v121, v121, 0
	v_accvgpr_read_b32 v116, a134
	v_add_f32_e32 v120, v122, v120
	v_add_f32_e32 v121, v123, v121
	s_waitcnt lgkmcnt(1)
	v_mfma_f32_32x32x16_bf16 a[64:79], v[198:201], v[96:99], a[64:79]
	v_accvgpr_read_b32 v122, a128
	v_accvgpr_read_b32 v119, a133
	v_accvgpr_read_b32 v118, a132
	v_accvgpr_read_b32 v133, a131
	v_accvgpr_read_b32 v132, a130
	v_accvgpr_read_b32 v123, a129
	v_add_f32_e32 v120, v124, v120
	v_add_f32_e32 v121, v125, v121
	s_waitcnt lgkmcnt(0)
	v_mfma_f32_32x32x16_bf16 a[96:111], v[202:205], v[96:99], a[96:111]
	v_fma_f32 v96, v100, s52, v30
	v_fma_f32 v97, v101, s52, v31
	v_fma_f32 v122, v122, s52, v30
	v_fma_f32 v123, v123, s52, v31
	v_fma_f32 v124, v132, s52, v30
	v_fma_f32 v125, v133, s52, v31
	v_fma_f32 v118, v118, s52, v30
	v_fma_f32 v119, v119, s52, v31
	v_exp_f32_e32 v122, v122
	v_exp_f32_e32 v123, v123
	v_exp_f32_e32 v124, v124
	v_mfma_f32_32x32x16_bf16 a[16:31], v[142:145], v[24:27], a[16:31]
	v_exp_f32_e32 v142, v96
	v_exp_f32_e32 v143, v97
	v_lshl_add_u64 v[96:97], s[36:37], 0, v[240:241]
	s_add_u32 s36, s8, s38
	s_addc_u32 s37, s9, 0
	global_load_dwordx4 v[100:103], v[96:97], off
	v_lshl_add_u64 v[96:97], s[36:37], 0, v[240:241]
	global_load_dwordx4 v[96:99], v[96:97], off
	v_mfma_f32_32x32x16_bf16 a[48:63], v[146:149], v[24:27], a[48:63]
	v_exp_f32_e32 v125, v125
	v_exp_f32_e32 v118, v118
	v_exp_f32_e32 v119, v119
	v_add_f32_e32 v120, v126, v120
	v_add_f32_e32 v121, v127, v121
	v_add_f32_e64 v126, v142, 0
	v_add_f32_e64 v127, v143, 0
	v_add_f32_e32 v20, v114, v20
	v_add_f32_e32 v21, v115, v21
	v_accvgpr_read_b32 v115, a137
	v_mfma_f32_32x32x16_bf16 a[80:95], v[150:153], v[24:27], a[80:95]
	v_accvgpr_read_b32 v114, a136
	v_accvgpr_read_b32 v109, a139
	v_accvgpr_read_b32 v108, a138
	v_accvgpr_read_b32 v111, a143
	v_accvgpr_read_b32 v110, a142
	v_accvgpr_read_b32 v113, a141
	v_accvgpr_read_b32 v112, a140
	v_mfma_f32_32x32x16_bf16 a[112:127], v[154:157], v[24:27], a[112:127]
	v_cvt_pk_bf16_f32 v24, v142, v143
	v_cvt_pk_bf16_f32 v25, v38, v39
	v_cvt_pk_bf16_f32 v26, v28, v29
	v_cvt_pk_bf16_f32 v27, v18, v19
	v_add_f32_e64 v38, v38, v126
	v_add_f32_e64 v39, v39, v127
	v_fma_f32 v108, v108, s52, v30
	v_fma_f32 v109, v109, s52, v31
	v_add_f32_e32 v28, v28, v38
	v_add_f32_e32 v29, v29, v39
	v_mfma_f32_32x32x16_bf16 a[16:31], v[158:161], v[24:27], a[16:31]
	v_fma_f32 v38, v114, s52, v30
	v_fma_f32 v39, v115, s52, v31
	v_add_f32_e64 v18, v18, v28
	v_add_f32_e64 v19, v19, v29
	v_exp_f32_e32 v38, v38
	v_exp_f32_e32 v39, v39
	v_add_f32_e64 v28, v122, 0
	v_add_f32_e64 v29, v123, 0
	v_exp_f32_e32 v114, v108
	v_exp_f32_e32 v115, v109
	v_mfma_f32_32x32x16_bf16 a[48:63], v[162:165], v[24:27], a[48:63]
	v_fma_f32 v112, v112, s52, v30
	v_fma_f32 v113, v113, s52, v31
	v_add_f32_e64 v28, v124, v28
	v_add_f32_e64 v29, v125, v29
	v_exp_f32_e32 v112, v112
	v_exp_f32_e32 v113, v113
	v_add_f32_e32 v28, v118, v28
	v_add_f32_e32 v29, v119, v29
	v_cvt_pk_bf16_f32 v108, v38, v39
	v_cvt_pk_bf16_f32 v109, v114, v115
	v_mfma_f32_32x32x16_bf16 a[80:95], v[166:169], v[24:27], a[80:95]
	v_mfma_f32_32x32x16_bf16 a[112:127], v[170:173], v[24:27], a[112:127]
	v_fma_f32 v24, v116, s52, v30
	v_fma_f32 v25, v117, s52, v31
	v_cvt_pk_bf16_f32 v26, v118, v119
	v_exp_f32_e32 v116, v24
	v_exp_f32_e32 v117, v25
	v_cvt_pk_bf16_f32 v24, v122, v123
	v_cvt_pk_bf16_f32 v25, v124, v125
	v_cvt_pk_bf16_f32 v27, v116, v117
	v_add_f32_e32 v28, v116, v28
	v_add_f32_e32 v29, v117, v29
	s_nop 0
	v_mfma_f32_32x32x16_bf16 a[16:31], v[174:177], v[24:27], a[16:31]
	v_add_f32_e64 v116, v38, 0
	v_add_f32_e64 v117, v39, 0
	v_add_f32_e64 v38, v114, v116
	v_add_f32_e64 v39, v115, v117
	v_mfma_f32_32x32x16_bf16 a[48:63], v[178:181], v[24:27], a[48:63]
	v_mfma_f32_32x32x16_bf16 a[80:95], v[182:185], v[24:27], a[80:95]
	v_mfma_f32_32x32x16_bf16 a[112:127], v[186:189], v[24:27], a[112:127]
	v_fma_f32 v24, v110, s52, v30
	v_fma_f32 v25, v111, s52, v31
	v_add_f32_e64 v26, v112, v38
	v_add_f32_e64 v27, v113, v39
	v_exp_f32_e32 v24, v24
	v_exp_f32_e32 v25, v25
	v_cvt_pk_bf16_f32 v110, v112, v113
	v_cvt_pk_bf16_f32 v111, v24, v25
	s_nop 1
	v_mfma_f32_32x32x16_bf16 a[16:31], v[190:193], v[108:111], a[16:31]
	v_add_f32_e64 v24, v24, v26
	v_add_f32_e64 v25, v25, v27
	v_mov_b32_e32 v26, v20
	v_mov_b32_e32 v27, v120
	v_mov_b32_e32 v120, v21
	v_add_f32_e32 v20, v26, v120
	v_add_f32_e32 v21, v27, v121
	v_mov_b32_e32 v26, v22
	v_mov_b32_e32 v27, v18
	v_mfma_f32_32x32x16_bf16 a[48:63], v[194:197], v[108:111], a[48:63]
	v_mov_b32_e32 v18, v23
	v_add_f32_e64 v20, v130, v20
	v_add_f32_e64 v21, v131, v21
	v_add_f32_e64 v18, v26, v18
	v_add_f32_e64 v19, v27, v19
	v_add_f32_e32 v18, v20, v18
	v_add_f32_e32 v19, v21, v19
	v_mov_b32_e32 v20, v36
	v_mov_b32_e32 v21, v28
	v_mfma_f32_32x32x16_bf16 a[80:95], v[198:201], v[108:111], a[80:95]
	v_mov_b32_e32 v28, v37
	v_add_f32_e64 v20, v20, v28
	v_add_f32_e64 v21, v21, v29
	v_add_f32_e64 v18, v20, v18
	v_add_f32_e64 v19, v21, v19
	v_mov_b32_e32 v20, v16
	v_mov_b32_e32 v21, v24
	v_mov_b32_e32 v24, v17
	v_mfma_f32_32x32x16_bf16 a[112:127], v[202:205], v[108:111], a[112:127]
	v_add_f32_e64 v16, v20, v24
	v_add_f32_e64 v17, v21, v25
	v_add_f32_e64 v130, v16, v18
	v_add_f32_e64 v131, v17, v19
